# K-loops: s_setprio 0 moved from before to after the phase-ending barrier, redundant compiler lgkmcnt(0) at MMA head deleted (28 sites each); on top of H7
# speedup vs baseline: 1.0166x; 1.0166x over previous
.LBB0_904:
	s_add_i32 s69, s8, 2
	s_add_u32 s0, s52, 0xfff80080
	s_addc_u32 s1, s53, -1
	s_add_i32 s70, 0, 0x10000
	s_cmp_eq_u32 s66, s8
	s_cselect_b32 s59, s41, s1
	s_cselect_b32 s58, s45, s0
	s_cselect_b32 s9, s43, s68
	s_cselect_b32 s8, s65, s67
	s_add_i32 s0, 0, 0x14000
	v_add_u32_e32 v156, s70, v141
	v_add_u32_e32 v172, s0, v141
	ds_read_b128 v[144:147], v156
	ds_read_b128 v[148:151], v156 offset:1024
	ds_read_b128 v[152:155], v156 offset:2048
	ds_read_b128 v[156:159], v156 offset:3072
	ds_read_b128 v[160:163], v172
	ds_read_b128 v[164:167], v172 offset:1024
	ds_read_b128 v[168:171], v172 offset:2048
	ds_read_b128 v[172:175], v172 offset:3072
	v_lshl_add_u64 v[214:215], s[52:53], 0, v[138:139]
	s_add_i32 m0, s27, 0xc000
	ds_read_b128 v[176:179], v143
	ds_read_b128 v[180:183], v143 offset:1024
	ds_read_b128 v[184:187], v143 offset:2048
	ds_read_b128 v[188:191], v143 offset:3072
	ds_read_b128 v[192:195], v143 offset:4096
	ds_read_b128 v[202:205], v143 offset:5120
	ds_read_b128 v[206:209], v143 offset:6144
	ds_read_b128 v[210:213], v143 offset:7168
	global_load_lds_dwordx4 v[214:215], off
	v_lshl_add_u64 v[214:215], s[52:53], 0, v[136:137]
	s_add_i32 m0, s27, 0xe000
	s_nop 0
	global_load_lds_dwordx4 v[214:215], off
	s_waitcnt vmcnt(8)
	s_waitcnt lgkmcnt(0)
	s_barrier
	s_setprio 1
	v_mfma_f32_16x16x32_bf16 v[126:129], v[144:147], v[176:179], v[126:129]
	v_mfma_f32_16x16x32_bf16 v[118:121], v[152:155], v[176:179], v[118:121]
	v_mfma_f32_16x16x32_bf16 v[110:113], v[144:147], v[184:187], v[110:113]
	v_mfma_f32_16x16x32_bf16 v[102:105], v[152:155], v[184:187], v[102:105]
	v_mfma_f32_16x16x32_bf16 v[94:97], v[144:147], v[192:195], v[94:97]
	v_mfma_f32_16x16x32_bf16 v[86:89], v[152:155], v[192:195], v[86:89]
	v_mfma_f32_16x16x32_bf16 v[78:81], v[144:147], v[206:209], v[78:81]
	v_mfma_f32_16x16x32_bf16 v[70:73], v[152:155], v[206:209], v[70:73]
	v_mfma_f32_16x16x32_bf16 v[126:129], v[148:151], v[180:183], v[126:129]
	v_mfma_f32_16x16x32_bf16 v[118:121], v[156:159], v[180:183], v[118:121]
	v_mfma_f32_16x16x32_bf16 v[110:113], v[148:151], v[188:191], v[110:113]
	v_mfma_f32_16x16x32_bf16 v[102:105], v[156:159], v[188:191], v[102:105]
	v_mfma_f32_16x16x32_bf16 v[94:97], v[148:151], v[202:205], v[94:97]
	v_mfma_f32_16x16x32_bf16 v[86:89], v[156:159], v[202:205], v[86:89]
	v_mfma_f32_16x16x32_bf16 v[78:81], v[148:151], v[210:213], v[78:81]
	v_mfma_f32_16x16x32_bf16 v[70:73], v[156:159], v[210:213], v[70:73]
	s_setprio 0
	s_setprio 1
	v_mfma_f32_16x16x32_bf16 v[122:125], v[160:163], v[176:179], v[122:125]
	v_mfma_f32_16x16x32_bf16 v[114:117], v[168:171], v[176:179], v[114:117]
	v_mfma_f32_16x16x32_bf16 v[106:109], v[160:163], v[184:187], v[106:109]
	v_mfma_f32_16x16x32_bf16 v[98:101], v[168:171], v[184:187], v[98:101]
	v_mfma_f32_16x16x32_bf16 v[90:93], v[160:163], v[192:195], v[90:93]
	v_mfma_f32_16x16x32_bf16 v[82:85], v[168:171], v[192:195], v[82:85]
	v_mfma_f32_16x16x32_bf16 v[74:77], v[160:163], v[206:209], v[74:77]
	v_mfma_f32_16x16x32_bf16 v[66:69], v[168:171], v[206:209], v[66:69]
	v_mfma_f32_16x16x32_bf16 v[122:125], v[164:167], v[180:183], v[122:125]
	v_mfma_f32_16x16x32_bf16 v[114:117], v[172:175], v[180:183], v[114:117]
	v_mfma_f32_16x16x32_bf16 v[106:109], v[164:167], v[188:191], v[106:109]
	v_mfma_f32_16x16x32_bf16 v[98:101], v[172:175], v[188:191], v[98:101]
	v_mfma_f32_16x16x32_bf16 v[90:93], v[164:167], v[202:205], v[90:93]
	v_mfma_f32_16x16x32_bf16 v[82:85], v[172:175], v[202:205], v[82:85]
	v_mfma_f32_16x16x32_bf16 v[74:77], v[164:167], v[210:213], v[74:77]
	v_mfma_f32_16x16x32_bf16 v[66:69], v[172:175], v[210:213], v[66:69]
	s_barrier
	s_setprio 0
	s_add_i32 s1, s70, s26
	v_lshl_add_u64 v[214:215], s[8:9], 0, v[196:197]
	s_mov_b32 m0, s1
	ds_read_b128 v[176:179], v143 offset:16384
	ds_read_b128 v[180:183], v143 offset:17408
	ds_read_b128 v[184:187], v143 offset:18432
	ds_read_b128 v[188:191], v143 offset:19456
	ds_read_b128 v[192:195], v143 offset:20480
	ds_read_b128 v[202:205], v143 offset:21504
	ds_read_b128 v[206:209], v143 offset:22528
	ds_read_b128 v[210:213], v143 offset:23552
	global_load_lds_dwordx4 v[214:215], off
	s_add_i32 m0, s1, 0x2000
	s_add_u32 s70, s8, 0x80000
	v_lshl_add_u64 v[216:217], s[8:9], 0, v[130:131]
	s_addc_u32 s71, s9, 0
	s_add_i32 s0, s0, s26
	global_load_lds_dwordx4 v[216:217], off
	v_lshl_add_u64 v[218:219], s[70:71], 0, v[196:197]
	s_mov_b32 m0, s0
	v_lshl_add_u64 v[220:221], s[58:59], 0, v[132:133]
	global_load_lds_dwordx4 v[218:219], off
	v_lshl_add_u64 v[218:219], s[70:71], 0, v[130:131]
	s_add_i32 m0, s0, 0x2000
	s_nop 0
	global_load_lds_dwordx4 v[218:219], off
	v_lshl_add_u64 v[218:219], s[58:59], 0, v[134:135]
	s_mov_b32 m0, s27
	s_nop 0
	global_load_lds_dwordx4 v[218:219], off
	s_mov_b32 m0, s28
	s_nop 0
	global_load_lds_dwordx4 v[220:221], off
	s_waitcnt vmcnt(8)
	s_waitcnt lgkmcnt(0)
	s_barrier
	s_setprio 1
	v_mfma_f32_16x16x32_bf16 v[62:65], v[144:147], v[176:179], v[62:65]
	v_mfma_f32_16x16x32_bf16 v[54:57], v[152:155], v[176:179], v[54:57]
	v_mfma_f32_16x16x32_bf16 v[46:49], v[144:147], v[184:187], v[46:49]
	v_mfma_f32_16x16x32_bf16 v[38:41], v[152:155], v[184:187], v[38:41]
	v_mfma_f32_16x16x32_bf16 v[30:33], v[144:147], v[192:195], v[30:33]
	v_mfma_f32_16x16x32_bf16 v[22:25], v[152:155], v[192:195], v[22:25]
	v_mfma_f32_16x16x32_bf16 v[14:17], v[144:147], v[206:209], v[14:17]
	v_mfma_f32_16x16x32_bf16 v[6:9], v[152:155], v[206:209], v[6:9]
	v_mfma_f32_16x16x32_bf16 v[62:65], v[148:151], v[180:183], v[62:65]
	v_mfma_f32_16x16x32_bf16 v[54:57], v[156:159], v[180:183], v[54:57]
	v_mfma_f32_16x16x32_bf16 v[46:49], v[148:151], v[188:191], v[46:49]
	v_mfma_f32_16x16x32_bf16 v[38:41], v[156:159], v[188:191], v[38:41]
	v_mfma_f32_16x16x32_bf16 v[30:33], v[148:151], v[202:205], v[30:33]
	v_mfma_f32_16x16x32_bf16 v[22:25], v[156:159], v[202:205], v[22:25]
	v_mfma_f32_16x16x32_bf16 v[14:17], v[148:151], v[210:213], v[14:17]
	v_mfma_f32_16x16x32_bf16 v[6:9], v[156:159], v[210:213], v[6:9]
	s_setprio 0
	s_setprio 1
	v_mfma_f32_16x16x32_bf16 v[58:61], v[160:163], v[176:179], v[58:61]
	v_mfma_f32_16x16x32_bf16 v[50:53], v[168:171], v[176:179], v[50:53]
	v_mfma_f32_16x16x32_bf16 v[42:45], v[160:163], v[184:187], v[42:45]
	v_mfma_f32_16x16x32_bf16 v[34:37], v[168:171], v[184:187], v[34:37]
	v_mfma_f32_16x16x32_bf16 v[26:29], v[160:163], v[192:195], v[26:29]
	v_mfma_f32_16x16x32_bf16 v[18:21], v[168:171], v[192:195], v[18:21]
	v_mfma_f32_16x16x32_bf16 v[10:13], v[160:163], v[206:209], v[10:13]
	v_mfma_f32_16x16x32_bf16 v[2:5], v[168:171], v[206:209], v[2:5]
	v_mfma_f32_16x16x32_bf16 v[58:61], v[164:167], v[180:183], v[58:61]
	v_mfma_f32_16x16x32_bf16 v[50:53], v[172:175], v[180:183], v[50:53]
	v_mfma_f32_16x16x32_bf16 v[42:45], v[164:167], v[188:191], v[42:45]
	v_mfma_f32_16x16x32_bf16 v[34:37], v[172:175], v[188:191], v[34:37]
	v_mfma_f32_16x16x32_bf16 v[26:29], v[164:167], v[202:205], v[26:29]
	v_mfma_f32_16x16x32_bf16 v[18:21], v[172:175], v[202:205], v[18:21]
	v_mfma_f32_16x16x32_bf16 v[10:13], v[164:167], v[210:213], v[10:13]
	v_mfma_f32_16x16x32_bf16 v[2:5], v[172:175], v[210:213], v[2:5]
	s_barrier
	s_setprio 0
	s_add_i32 s0, 0, 0x18000
	s_add_i32 s1, 0, 0x1c000
	v_add_u32_e32 v156, s0, v141
	v_add_u32_e32 v172, s1, v141
	ds_read_b128 v[144:147], v156
	ds_read_b128 v[148:151], v156 offset:1024
	ds_read_b128 v[152:155], v156 offset:2048
	ds_read_b128 v[156:159], v156 offset:3072
	ds_read_b128 v[160:163], v172
	ds_read_b128 v[164:167], v172 offset:1024
	ds_read_b128 v[168:171], v172 offset:2048
	ds_read_b128 v[172:175], v172 offset:3072
	s_add_u32 s58, s58, 0x80000
	s_addc_u32 s59, s59, 0
	s_mov_b32 m0, s29
	v_lshl_add_u64 v[222:223], s[58:59], 0, v[134:135]
	ds_read_b128 v[176:179], v143 offset:32768
	ds_read_b128 v[180:183], v143 offset:33792
	ds_read_b128 v[184:187], v143 offset:34816
	ds_read_b128 v[188:191], v143 offset:35840
	ds_read_b128 v[192:195], v143 offset:36864
	ds_read_b128 v[202:205], v143 offset:37888
	ds_read_b128 v[206:209], v143 offset:38912
	ds_read_b128 v[210:213], v143 offset:39936
	global_load_lds_dwordx4 v[222:223], off
	v_lshl_add_u64 v[222:223], s[58:59], 0, v[132:133]
	s_mov_b32 m0, s30
	s_nop 0
	global_load_lds_dwordx4 v[222:223], off
	s_waitcnt vmcnt(8)
	s_waitcnt lgkmcnt(0)
	s_barrier
	s_setprio 1
	v_mfma_f32_16x16x32_bf16 v[126:129], v[144:147], v[176:179], v[126:129]
	v_mfma_f32_16x16x32_bf16 v[118:121], v[152:155], v[176:179], v[118:121]
	v_mfma_f32_16x16x32_bf16 v[110:113], v[144:147], v[184:187], v[110:113]
	v_mfma_f32_16x16x32_bf16 v[102:105], v[152:155], v[184:187], v[102:105]
	v_mfma_f32_16x16x32_bf16 v[94:97], v[144:147], v[192:195], v[94:97]
	v_mfma_f32_16x16x32_bf16 v[86:89], v[152:155], v[192:195], v[86:89]
	v_mfma_f32_16x16x32_bf16 v[78:81], v[144:147], v[206:209], v[78:81]
	v_mfma_f32_16x16x32_bf16 v[70:73], v[152:155], v[206:209], v[70:73]
	v_mfma_f32_16x16x32_bf16 v[126:129], v[148:151], v[180:183], v[126:129]
	v_mfma_f32_16x16x32_bf16 v[118:121], v[156:159], v[180:183], v[118:121]
	v_mfma_f32_16x16x32_bf16 v[110:113], v[148:151], v[188:191], v[110:113]
	v_mfma_f32_16x16x32_bf16 v[102:105], v[156:159], v[188:191], v[102:105]
	v_mfma_f32_16x16x32_bf16 v[94:97], v[148:151], v[202:205], v[94:97]
	v_mfma_f32_16x16x32_bf16 v[86:89], v[156:159], v[202:205], v[86:89]
	v_mfma_f32_16x16x32_bf16 v[78:81], v[148:151], v[210:213], v[78:81]
	v_mfma_f32_16x16x32_bf16 v[70:73], v[156:159], v[210:213], v[70:73]
	s_setprio 0
	s_setprio 1
	v_mfma_f32_16x16x32_bf16 v[122:125], v[160:163], v[176:179], v[122:125]
	v_mfma_f32_16x16x32_bf16 v[114:117], v[168:171], v[176:179], v[114:117]
	v_mfma_f32_16x16x32_bf16 v[106:109], v[160:163], v[184:187], v[106:109]
	v_mfma_f32_16x16x32_bf16 v[98:101], v[168:171], v[184:187], v[98:101]
	v_mfma_f32_16x16x32_bf16 v[90:93], v[160:163], v[192:195], v[90:93]
	v_mfma_f32_16x16x32_bf16 v[82:85], v[168:171], v[192:195], v[82:85]
	v_mfma_f32_16x16x32_bf16 v[74:77], v[160:163], v[206:209], v[74:77]
	v_mfma_f32_16x16x32_bf16 v[66:69], v[168:171], v[206:209], v[66:69]
	v_mfma_f32_16x16x32_bf16 v[122:125], v[164:167], v[180:183], v[122:125]
	v_mfma_f32_16x16x32_bf16 v[114:117], v[172:175], v[180:183], v[114:117]
	v_mfma_f32_16x16x32_bf16 v[106:109], v[164:167], v[188:191], v[106:109]
	v_mfma_f32_16x16x32_bf16 v[98:101], v[172:175], v[188:191], v[98:101]
	v_mfma_f32_16x16x32_bf16 v[90:93], v[164:167], v[202:205], v[90:93]
	v_mfma_f32_16x16x32_bf16 v[82:85], v[172:175], v[202:205], v[82:85]
	v_mfma_f32_16x16x32_bf16 v[74:77], v[164:167], v[210:213], v[74:77]
	v_mfma_f32_16x16x32_bf16 v[66:69], v[172:175], v[210:213], v[66:69]
	s_barrier
	s_setprio 0
	s_add_i32 s0, s0, s26
	v_lshl_add_u64 v[214:215], v[214:215], 0, s[16:17]
	s_mov_b32 m0, s0
	ds_read_b128 v[176:179], v143 offset:49152
	ds_read_b128 v[180:183], v143 offset:50176
	ds_read_b128 v[184:187], v143 offset:51200
	ds_read_b128 v[188:191], v143 offset:52224
	ds_read_b128 v[192:195], v143 offset:53248
	ds_read_b128 v[202:205], v143 offset:54272
	ds_read_b128 v[206:209], v143 offset:55296
	ds_read_b128 v[210:213], v143 offset:56320
	global_load_lds_dwordx4 v[214:215], off
	s_add_i32 m0, s0, 0x2000
	s_add_u32 s8, s8, 0x80080
	v_lshl_add_u64 v[214:215], v[216:217], 0, s[16:17]
	s_addc_u32 s9, s9, 0
	s_add_i32 s0, s1, s26
	global_load_lds_dwordx4 v[214:215], off
	v_lshl_add_u64 v[214:215], s[8:9], 0, v[196:197]
	s_mov_b32 m0, s0
	s_nop 0
	global_load_lds_dwordx4 v[214:215], off
	v_lshl_add_u64 v[214:215], s[8:9], 0, v[130:131]
	s_add_i32 m0, s0, 0x2000
	s_nop 0
	global_load_lds_dwordx4 v[214:215], off
	v_lshl_add_u64 v[214:215], v[218:219], 0, s[16:17]
	s_mov_b32 m0, s31
	s_nop 0
	global_load_lds_dwordx4 v[214:215], off
	v_lshl_add_u64 v[214:215], v[220:221], 0, s[16:17]
	s_mov_b32 m0, s34
	s_nop 0
	global_load_lds_dwordx4 v[214:215], off
	s_waitcnt vmcnt(8)
	s_waitcnt lgkmcnt(0)
	s_barrier
	s_setprio 1
	v_mfma_f32_16x16x32_bf16 v[62:65], v[144:147], v[176:179], v[62:65]
	v_mfma_f32_16x16x32_bf16 v[54:57], v[152:155], v[176:179], v[54:57]
	v_mfma_f32_16x16x32_bf16 v[46:49], v[144:147], v[184:187], v[46:49]
	v_mfma_f32_16x16x32_bf16 v[38:41], v[152:155], v[184:187], v[38:41]
	v_mfma_f32_16x16x32_bf16 v[30:33], v[144:147], v[192:195], v[30:33]
	v_mfma_f32_16x16x32_bf16 v[22:25], v[152:155], v[192:195], v[22:25]
	v_mfma_f32_16x16x32_bf16 v[14:17], v[144:147], v[206:209], v[14:17]
	v_mfma_f32_16x16x32_bf16 v[6:9], v[152:155], v[206:209], v[6:9]
	v_mfma_f32_16x16x32_bf16 v[62:65], v[148:151], v[180:183], v[62:65]
	v_mfma_f32_16x16x32_bf16 v[54:57], v[156:159], v[180:183], v[54:57]
	v_mfma_f32_16x16x32_bf16 v[46:49], v[148:151], v[188:191], v[46:49]
	v_mfma_f32_16x16x32_bf16 v[38:41], v[156:159], v[188:191], v[38:41]
	v_mfma_f32_16x16x32_bf16 v[30:33], v[148:151], v[202:205], v[30:33]
	v_mfma_f32_16x16x32_bf16 v[22:25], v[156:159], v[202:205], v[22:25]
	v_mfma_f32_16x16x32_bf16 v[14:17], v[148:151], v[210:213], v[14:17]
	v_mfma_f32_16x16x32_bf16 v[6:9], v[156:159], v[210:213], v[6:9]
	s_setprio 0
	s_setprio 1
	v_mfma_f32_16x16x32_bf16 v[58:61], v[160:163], v[176:179], v[58:61]
	v_mfma_f32_16x16x32_bf16 v[50:53], v[168:171], v[176:179], v[50:53]
	v_mfma_f32_16x16x32_bf16 v[42:45], v[160:163], v[184:187], v[42:45]
	v_mfma_f32_16x16x32_bf16 v[34:37], v[168:171], v[184:187], v[34:37]
	v_mfma_f32_16x16x32_bf16 v[26:29], v[160:163], v[192:195], v[26:29]
	v_mfma_f32_16x16x32_bf16 v[18:21], v[168:171], v[192:195], v[18:21]
	v_mfma_f32_16x16x32_bf16 v[10:13], v[160:163], v[206:209], v[10:13]
	v_mfma_f32_16x16x32_bf16 v[2:5], v[168:171], v[206:209], v[2:5]
	v_mfma_f32_16x16x32_bf16 v[58:61], v[164:167], v[180:183], v[58:61]
	v_mfma_f32_16x16x32_bf16 v[50:53], v[172:175], v[180:183], v[50:53]
	v_mfma_f32_16x16x32_bf16 v[42:45], v[164:167], v[188:191], v[42:45]
	v_mfma_f32_16x16x32_bf16 v[34:37], v[172:175], v[188:191], v[34:37]
	v_mfma_f32_16x16x32_bf16 v[26:29], v[164:167], v[202:205], v[26:29]
	v_mfma_f32_16x16x32_bf16 v[18:21], v[172:175], v[202:205], v[18:21]
	v_mfma_f32_16x16x32_bf16 v[10:13], v[164:167], v[210:213], v[10:13]
	v_mfma_f32_16x16x32_bf16 v[2:5], v[172:175], v[210:213], v[2:5]
	s_barrier
	s_setprio 0
	s_add_u32 s67, s67, 0x100
	s_addc_u32 s68, s68, 0
	s_add_u32 s52, s52, 0x100
	s_addc_u32 s53, s53, 0
	s_cmp_ge_i32 s69, s62
	s_mov_b32 s8, s69
	s_cbranch_scc0 .LBB0_904
	s_and_b64 vcc, exec, s[38:39]
	s_cbranch_vccz .LBB0_907
	s_barrier

.LBB0_987:
	s_add_i32 s72, s50, 2
	s_add_u32 s8, s48, 0x100
	s_addc_u32 s9, s49, 0
	s_add_i32 s0, 0, 0x10000
	s_cmp_eq_u32 s41, s50
	s_cselect_b32 s53, s45, s9
	s_cselect_b32 s52, s44, s8
	s_cselect_b32 s51, s47, s71
	s_cselect_b32 s50, s46, s70
	s_add_i32 s1, 0, 0x14000
	v_add_u32_e32 v142, s0, v188
	v_add_u32_e32 v172, s1, v188
	ds_read_b128 v[130:133], v142
	ds_read_b128 v[134:137], v142 offset:1024
	ds_read_b128 v[138:141], v142 offset:2048
	ds_read_b128 v[142:145], v142 offset:3072
	ds_read_b128 v[146:149], v172
	ds_read_b128 v[164:167], v172 offset:1024
	ds_read_b128 v[168:171], v172 offset:2048
	ds_read_b128 v[172:175], v172 offset:3072
	v_lshl_add_u64 v[194:195], s[48:49], 0, v[162:163]
	s_add_i32 m0, s27, 0xc000
	ds_read_b128 v[176:179], v189
	ds_read_b128 v[180:183], v189 offset:1024
	ds_read_b128 v[184:187], v189 offset:2048
	ds_read_b128 v[190:193], v189 offset:3072
	ds_read_b128 v[202:205], v189 offset:4096
	ds_read_b128 v[206:209], v189 offset:5120
	ds_read_b128 v[210:213], v189 offset:6144
	ds_read_b128 v[214:217], v189 offset:7168
	global_load_lds_dwordx4 v[194:195], off
	v_lshl_add_u64 v[194:195], s[48:49], 0, v[160:161]
	s_add_i32 m0, s27, 0xe000
	s_nop 0
	global_load_lds_dwordx4 v[194:195], off
	s_waitcnt vmcnt(8)
	s_waitcnt lgkmcnt(0)
	s_barrier
	s_setprio 1
	v_mfma_f32_16x16x32_bf16 v[126:129], v[130:133], v[176:179], v[126:129]
	v_mfma_f32_16x16x32_bf16 v[122:125], v[138:141], v[176:179], v[122:125]
	v_mfma_f32_16x16x32_bf16 v[110:113], v[130:133], v[184:187], v[110:113]
	v_mfma_f32_16x16x32_bf16 v[106:109], v[138:141], v[184:187], v[106:109]
	v_mfma_f32_16x16x32_bf16 v[98:101], v[130:133], v[202:205], v[98:101]
	v_mfma_f32_16x16x32_bf16 v[90:93], v[138:141], v[202:205], v[90:93]
	v_mfma_f32_16x16x32_bf16 v[82:85], v[130:133], v[210:213], v[82:85]
	v_mfma_f32_16x16x32_bf16 v[74:77], v[138:141], v[210:213], v[74:77]
	v_mfma_f32_16x16x32_bf16 v[126:129], v[134:137], v[180:183], v[126:129]
	v_mfma_f32_16x16x32_bf16 v[122:125], v[142:145], v[180:183], v[122:125]
	v_mfma_f32_16x16x32_bf16 v[110:113], v[134:137], v[190:193], v[110:113]
	v_mfma_f32_16x16x32_bf16 v[106:109], v[142:145], v[190:193], v[106:109]
	v_mfma_f32_16x16x32_bf16 v[98:101], v[134:137], v[206:209], v[98:101]
	v_mfma_f32_16x16x32_bf16 v[90:93], v[142:145], v[206:209], v[90:93]
	v_mfma_f32_16x16x32_bf16 v[82:85], v[134:137], v[214:217], v[82:85]
	v_mfma_f32_16x16x32_bf16 v[74:77], v[142:145], v[214:217], v[74:77]
	s_setprio 0
	s_setprio 1
	v_mfma_f32_16x16x32_bf16 v[118:121], v[146:149], v[176:179], v[118:121]
	v_mfma_f32_16x16x32_bf16 v[114:117], v[168:171], v[176:179], v[114:117]
	v_mfma_f32_16x16x32_bf16 v[102:105], v[146:149], v[184:187], v[102:105]
	v_mfma_f32_16x16x32_bf16 v[94:97], v[168:171], v[184:187], v[94:97]
	v_mfma_f32_16x16x32_bf16 v[86:89], v[146:149], v[202:205], v[86:89]
	v_mfma_f32_16x16x32_bf16 v[78:81], v[168:171], v[202:205], v[78:81]
	v_mfma_f32_16x16x32_bf16 v[70:73], v[146:149], v[210:213], v[70:73]
	v_mfma_f32_16x16x32_bf16 v[66:69], v[168:171], v[210:213], v[66:69]
	v_mfma_f32_16x16x32_bf16 v[118:121], v[164:167], v[180:183], v[118:121]
	v_mfma_f32_16x16x32_bf16 v[114:117], v[172:175], v[180:183], v[114:117]
	v_mfma_f32_16x16x32_bf16 v[102:105], v[164:167], v[190:193], v[102:105]
	v_mfma_f32_16x16x32_bf16 v[94:97], v[172:175], v[190:193], v[94:97]
	v_mfma_f32_16x16x32_bf16 v[86:89], v[164:167], v[206:209], v[86:89]
	v_mfma_f32_16x16x32_bf16 v[78:81], v[172:175], v[206:209], v[78:81]
	v_mfma_f32_16x16x32_bf16 v[70:73], v[164:167], v[214:217], v[70:73]
	v_mfma_f32_16x16x32_bf16 v[66:69], v[172:175], v[214:217], v[66:69]
	s_barrier
	s_setprio 0
	s_add_i32 s0, s0, s26
	v_lshl_add_u64 v[194:195], s[50:51], 0, v[196:197]
	s_mov_b32 m0, s0
	ds_read_b128 v[176:179], v189 offset:16384
	ds_read_b128 v[180:183], v189 offset:17408
	ds_read_b128 v[184:187], v189 offset:18432
	ds_read_b128 v[190:193], v189 offset:19456
	ds_read_b128 v[202:205], v189 offset:20480
	ds_read_b128 v[206:209], v189 offset:21504
	ds_read_b128 v[210:213], v189 offset:22528
	ds_read_b128 v[214:217], v189 offset:23552
	global_load_lds_dwordx4 v[194:195], off
	s_add_i32 m0, s0, 0x2000
	s_add_u32 s48, s50, 0x158000
	v_lshl_add_u64 v[218:219], s[50:51], 0, v[154:155]
	s_addc_u32 s49, s51, 0
	s_add_i32 s0, s1, s26
	global_load_lds_dwordx4 v[218:219], off
	v_lshl_add_u64 v[220:221], s[48:49], 0, v[196:197]
	s_mov_b32 m0, s0
	v_lshl_add_u64 v[222:223], s[52:53], 0, v[152:153]
	global_load_lds_dwordx4 v[220:221], off
	v_lshl_add_u64 v[220:221], s[48:49], 0, v[154:155]
	s_add_i32 m0, s0, 0x2000
	s_nop 0
	global_load_lds_dwordx4 v[220:221], off
	v_lshl_add_u64 v[220:221], s[52:53], 0, v[150:151]
	s_mov_b32 m0, s27
	s_nop 0
	global_load_lds_dwordx4 v[220:221], off
	s_mov_b32 m0, s28
	s_nop 0
	global_load_lds_dwordx4 v[222:223], off
	s_waitcnt vmcnt(8)
	s_waitcnt lgkmcnt(0)
	s_barrier
	s_setprio 1
	v_mfma_f32_16x16x32_bf16 v[62:65], v[130:133], v[176:179], v[62:65]
	v_mfma_f32_16x16x32_bf16 v[58:61], v[138:141], v[176:179], v[58:61]
	v_mfma_f32_16x16x32_bf16 v[50:53], v[130:133], v[184:187], v[50:53]
	v_mfma_f32_16x16x32_bf16 v[42:45], v[138:141], v[184:187], v[42:45]
	v_mfma_f32_16x16x32_bf16 v[34:37], v[130:133], v[202:205], v[34:37]
	v_mfma_f32_16x16x32_bf16 v[26:29], v[138:141], v[202:205], v[26:29]
	v_mfma_f32_16x16x32_bf16 v[18:21], v[130:133], v[210:213], v[18:21]
	v_mfma_f32_16x16x32_bf16 v[10:13], v[138:141], v[210:213], v[10:13]
	v_mfma_f32_16x16x32_bf16 v[62:65], v[134:137], v[180:183], v[62:65]
	v_mfma_f32_16x16x32_bf16 v[58:61], v[142:145], v[180:183], v[58:61]
	v_mfma_f32_16x16x32_bf16 v[50:53], v[134:137], v[190:193], v[50:53]
	v_mfma_f32_16x16x32_bf16 v[42:45], v[142:145], v[190:193], v[42:45]
	v_mfma_f32_16x16x32_bf16 v[34:37], v[134:137], v[206:209], v[34:37]
	v_mfma_f32_16x16x32_bf16 v[26:29], v[142:145], v[206:209], v[26:29]
	v_mfma_f32_16x16x32_bf16 v[18:21], v[134:137], v[214:217], v[18:21]
	v_mfma_f32_16x16x32_bf16 v[10:13], v[142:145], v[214:217], v[10:13]
	s_setprio 0
	s_setprio 1
	v_mfma_f32_16x16x32_bf16 v[54:57], v[146:149], v[176:179], v[54:57]
	v_mfma_f32_16x16x32_bf16 v[46:49], v[168:171], v[176:179], v[46:49]
	v_mfma_f32_16x16x32_bf16 v[38:41], v[146:149], v[184:187], v[38:41]
	v_mfma_f32_16x16x32_bf16 v[30:33], v[168:171], v[184:187], v[30:33]
	v_mfma_f32_16x16x32_bf16 v[22:25], v[146:149], v[202:205], v[22:25]
	v_mfma_f32_16x16x32_bf16 v[14:17], v[168:171], v[202:205], v[14:17]
	v_mfma_f32_16x16x32_bf16 v[6:9], v[146:149], v[210:213], v[6:9]
	v_mfma_f32_16x16x32_bf16 v[2:5], v[168:171], v[210:213], v[2:5]
	v_mfma_f32_16x16x32_bf16 v[54:57], v[164:167], v[180:183], v[54:57]
	v_mfma_f32_16x16x32_bf16 v[46:49], v[172:175], v[180:183], v[46:49]
	v_mfma_f32_16x16x32_bf16 v[38:41], v[164:167], v[190:193], v[38:41]
	v_mfma_f32_16x16x32_bf16 v[30:33], v[172:175], v[190:193], v[30:33]
	v_mfma_f32_16x16x32_bf16 v[22:25], v[164:167], v[206:209], v[22:25]
	v_mfma_f32_16x16x32_bf16 v[14:17], v[172:175], v[206:209], v[14:17]
	v_mfma_f32_16x16x32_bf16 v[6:9], v[164:167], v[214:217], v[6:9]
	v_mfma_f32_16x16x32_bf16 v[2:5], v[172:175], v[214:217], v[2:5]
	s_barrier
	s_setprio 0
	s_add_i32 s0, 0, 0x18000
	s_add_i32 s1, 0, 0x1c000
	v_add_u32_e32 v142, s0, v188
	v_add_u32_e32 v172, s1, v188
	ds_read_b128 v[130:133], v142
	ds_read_b128 v[134:137], v142 offset:1024
	ds_read_b128 v[138:141], v142 offset:2048
	ds_read_b128 v[142:145], v142 offset:3072
	ds_read_b128 v[146:149], v172
	ds_read_b128 v[164:167], v172 offset:1024
	ds_read_b128 v[168:171], v172 offset:2048
	ds_read_b128 v[172:175], v172 offset:3072
	s_add_u32 s48, s52, 0x158000
	s_addc_u32 s49, s53, 0
	s_mov_b32 m0, s29
	v_lshl_add_u64 v[224:225], s[48:49], 0, v[150:151]
	ds_read_b128 v[176:179], v189 offset:32768
	ds_read_b128 v[180:183], v189 offset:33792
	ds_read_b128 v[184:187], v189 offset:34816
	ds_read_b128 v[190:193], v189 offset:35840
	ds_read_b128 v[202:205], v189 offset:36864
	ds_read_b128 v[206:209], v189 offset:37888
	ds_read_b128 v[210:213], v189 offset:38912
	ds_read_b128 v[214:217], v189 offset:39936
	global_load_lds_dwordx4 v[224:225], off
	v_lshl_add_u64 v[224:225], s[48:49], 0, v[152:153]
	s_mov_b32 m0, s30
	s_nop 0
	global_load_lds_dwordx4 v[224:225], off
	s_waitcnt vmcnt(8)
	s_waitcnt lgkmcnt(0)
	s_barrier
	s_setprio 1
	v_mfma_f32_16x16x32_bf16 v[126:129], v[130:133], v[176:179], v[126:129]
	v_mfma_f32_16x16x32_bf16 v[122:125], v[138:141], v[176:179], v[122:125]
	v_mfma_f32_16x16x32_bf16 v[110:113], v[130:133], v[184:187], v[110:113]
	v_mfma_f32_16x16x32_bf16 v[106:109], v[138:141], v[184:187], v[106:109]
	v_mfma_f32_16x16x32_bf16 v[98:101], v[130:133], v[202:205], v[98:101]
	v_mfma_f32_16x16x32_bf16 v[90:93], v[138:141], v[202:205], v[90:93]
	v_mfma_f32_16x16x32_bf16 v[82:85], v[130:133], v[210:213], v[82:85]
	v_mfma_f32_16x16x32_bf16 v[74:77], v[138:141], v[210:213], v[74:77]
	v_mfma_f32_16x16x32_bf16 v[126:129], v[134:137], v[180:183], v[126:129]
	v_mfma_f32_16x16x32_bf16 v[122:125], v[142:145], v[180:183], v[122:125]
	v_mfma_f32_16x16x32_bf16 v[110:113], v[134:137], v[190:193], v[110:113]
	v_mfma_f32_16x16x32_bf16 v[106:109], v[142:145], v[190:193], v[106:109]
	v_mfma_f32_16x16x32_bf16 v[98:101], v[134:137], v[206:209], v[98:101]
	v_mfma_f32_16x16x32_bf16 v[90:93], v[142:145], v[206:209], v[90:93]
	v_mfma_f32_16x16x32_bf16 v[82:85], v[134:137], v[214:217], v[82:85]
	v_mfma_f32_16x16x32_bf16 v[74:77], v[142:145], v[214:217], v[74:77]
	s_setprio 0
	s_setprio 1
	v_mfma_f32_16x16x32_bf16 v[118:121], v[146:149], v[176:179], v[118:121]
	v_mfma_f32_16x16x32_bf16 v[114:117], v[168:171], v[176:179], v[114:117]
	v_mfma_f32_16x16x32_bf16 v[102:105], v[146:149], v[184:187], v[102:105]
	v_mfma_f32_16x16x32_bf16 v[94:97], v[168:171], v[184:187], v[94:97]
	v_mfma_f32_16x16x32_bf16 v[86:89], v[146:149], v[202:205], v[86:89]
	v_mfma_f32_16x16x32_bf16 v[78:81], v[168:171], v[202:205], v[78:81]
	v_mfma_f32_16x16x32_bf16 v[70:73], v[146:149], v[210:213], v[70:73]
	v_mfma_f32_16x16x32_bf16 v[66:69], v[168:171], v[210:213], v[66:69]
	v_mfma_f32_16x16x32_bf16 v[118:121], v[164:167], v[180:183], v[118:121]
	v_mfma_f32_16x16x32_bf16 v[114:117], v[172:175], v[180:183], v[114:117]
	v_mfma_f32_16x16x32_bf16 v[102:105], v[164:167], v[190:193], v[102:105]
	v_mfma_f32_16x16x32_bf16 v[94:97], v[172:175], v[190:193], v[94:97]
	v_mfma_f32_16x16x32_bf16 v[86:89], v[164:167], v[206:209], v[86:89]
	v_mfma_f32_16x16x32_bf16 v[78:81], v[172:175], v[206:209], v[78:81]
	v_mfma_f32_16x16x32_bf16 v[70:73], v[164:167], v[214:217], v[70:73]
	v_mfma_f32_16x16x32_bf16 v[66:69], v[172:175], v[214:217], v[66:69]
	s_barrier
	s_setprio 0
	s_add_i32 s0, s0, s26
	v_lshl_add_u64 v[194:195], v[194:195], 0, s[16:17]
	s_mov_b32 m0, s0
	ds_read_b128 v[176:179], v189 offset:49152
	ds_read_b128 v[180:183], v189 offset:50176
	ds_read_b128 v[184:187], v189 offset:51200
	ds_read_b128 v[190:193], v189 offset:52224
	ds_read_b128 v[202:205], v189 offset:53248
	ds_read_b128 v[206:209], v189 offset:54272
	ds_read_b128 v[210:213], v189 offset:55296
	ds_read_b128 v[214:217], v189 offset:56320
	global_load_lds_dwordx4 v[194:195], off
	s_add_i32 m0, s0, 0x2000
	s_add_u32 s48, s50, 0x158080
	v_lshl_add_u64 v[194:195], v[218:219], 0, s[16:17]
	s_addc_u32 s49, s51, 0
	s_add_i32 s0, s1, s26
	global_load_lds_dwordx4 v[194:195], off
	v_lshl_add_u64 v[194:195], s[48:49], 0, v[196:197]
	s_mov_b32 m0, s0
	s_nop 0
	global_load_lds_dwordx4 v[194:195], off
	v_lshl_add_u64 v[194:195], s[48:49], 0, v[154:155]
	s_add_i32 m0, s0, 0x2000
	s_nop 0
	global_load_lds_dwordx4 v[194:195], off
	v_lshl_add_u64 v[194:195], v[220:221], 0, s[16:17]
	s_mov_b32 m0, s35
	s_nop 0
	global_load_lds_dwordx4 v[194:195], off
	v_lshl_add_u64 v[194:195], v[222:223], 0, s[16:17]
	s_mov_b32 m0, s58
	s_nop 0
	global_load_lds_dwordx4 v[194:195], off
	s_waitcnt vmcnt(8)
	s_waitcnt lgkmcnt(0)
	s_barrier
	s_setprio 1
	v_mfma_f32_16x16x32_bf16 v[62:65], v[130:133], v[176:179], v[62:65]
	v_mfma_f32_16x16x32_bf16 v[58:61], v[138:141], v[176:179], v[58:61]
	v_mfma_f32_16x16x32_bf16 v[50:53], v[130:133], v[184:187], v[50:53]
	v_mfma_f32_16x16x32_bf16 v[42:45], v[138:141], v[184:187], v[42:45]
	v_mfma_f32_16x16x32_bf16 v[34:37], v[130:133], v[202:205], v[34:37]
	v_mfma_f32_16x16x32_bf16 v[26:29], v[138:141], v[202:205], v[26:29]
	v_mfma_f32_16x16x32_bf16 v[18:21], v[130:133], v[210:213], v[18:21]
	v_mfma_f32_16x16x32_bf16 v[10:13], v[138:141], v[210:213], v[10:13]
	v_mfma_f32_16x16x32_bf16 v[62:65], v[134:137], v[180:183], v[62:65]
	v_mfma_f32_16x16x32_bf16 v[58:61], v[142:145], v[180:183], v[58:61]
	v_mfma_f32_16x16x32_bf16 v[50:53], v[134:137], v[190:193], v[50:53]
	v_mfma_f32_16x16x32_bf16 v[42:45], v[142:145], v[190:193], v[42:45]
	v_mfma_f32_16x16x32_bf16 v[34:37], v[134:137], v[206:209], v[34:37]
	v_mfma_f32_16x16x32_bf16 v[26:29], v[142:145], v[206:209], v[26:29]
	v_mfma_f32_16x16x32_bf16 v[18:21], v[134:137], v[214:217], v[18:21]
	v_mfma_f32_16x16x32_bf16 v[10:13], v[142:145], v[214:217], v[10:13]
	s_setprio 0
	s_setprio 1
	v_mfma_f32_16x16x32_bf16 v[54:57], v[146:149], v[176:179], v[54:57]
	v_mfma_f32_16x16x32_bf16 v[46:49], v[168:171], v[176:179], v[46:49]
	v_mfma_f32_16x16x32_bf16 v[38:41], v[146:149], v[184:187], v[38:41]
	v_mfma_f32_16x16x32_bf16 v[30:33], v[168:171], v[184:187], v[30:33]
	v_mfma_f32_16x16x32_bf16 v[22:25], v[146:149], v[202:205], v[22:25]
	v_mfma_f32_16x16x32_bf16 v[14:17], v[168:171], v[202:205], v[14:17]
	v_mfma_f32_16x16x32_bf16 v[6:9], v[146:149], v[210:213], v[6:9]
	v_mfma_f32_16x16x32_bf16 v[2:5], v[168:171], v[210:213], v[2:5]
	v_mfma_f32_16x16x32_bf16 v[54:57], v[164:167], v[180:183], v[54:57]
	v_mfma_f32_16x16x32_bf16 v[46:49], v[172:175], v[180:183], v[46:49]
	v_mfma_f32_16x16x32_bf16 v[38:41], v[164:167], v[190:193], v[38:41]
	v_mfma_f32_16x16x32_bf16 v[30:33], v[172:175], v[190:193], v[30:33]
	v_mfma_f32_16x16x32_bf16 v[22:25], v[164:167], v[206:209], v[22:25]
	v_mfma_f32_16x16x32_bf16 v[14:17], v[172:175], v[206:209], v[14:17]
	v_mfma_f32_16x16x32_bf16 v[6:9], v[164:167], v[214:217], v[6:9]
	v_mfma_f32_16x16x32_bf16 v[2:5], v[172:175], v[214:217], v[2:5]
	s_barrier
	s_setprio 0
	s_add_u32 s70, s70, 0x100
	s_addc_u32 s71, s71, 0
	s_cmp_ge_i32 s72, s69
	s_mov_b64 s[48:49], s[8:9]
	s_mov_b32 s50, s72
	s_cbranch_scc0 .LBB0_987
	s_and_b64 vcc, exec, s[38:39]
	s_cbranch_vccz .LBB0_990
	s_barrier

.LBB0_1135:
	s_add_i32 s71, s8, 2
	s_add_u32 s0, s58, 0xfff80080
	s_addc_u32 s1, s59, -1
	s_add_i32 s72, 0, 0x10000
	s_cmp_eq_u32 s68, s8
	s_cselect_b32 s63, s43, s1
	s_cselect_b32 s62, s47, s0
	v_add_u32_e32 v146, s72, v149
	s_cselect_b32 s9, s45, s70
	s_cselect_b32 s8, s67, s69
	s_add_i32 s0, 0, 0x14000
	ds_read_b128 v[142:145], v146
	ds_read_b128 v[152:155], v146 offset:1024
	ds_read_b128 v[156:159], v146 offset:2048
	ds_read_b128 v[160:163], v146 offset:3072
	v_add_u32_e32 v146, s0, v149
	ds_read_b128 v[164:167], v146
	ds_read_b128 v[168:171], v146 offset:1024
	ds_read_b128 v[172:175], v146 offset:2048
	ds_read_b128 v[176:179], v146 offset:3072
	v_lshl_add_u64 v[146:147], s[58:59], 0, v[140:141]
	s_add_i32 m0, s27, 0xc000
	ds_read_b128 v[180:183], v151
	ds_read_b128 v[184:187], v151 offset:1024
	ds_read_b128 v[188:191], v151 offset:2048
	ds_read_b128 v[192:195], v151 offset:3072
	ds_read_b128 v[202:205], v151 offset:4096
	ds_read_b128 v[206:209], v151 offset:5120
	ds_read_b128 v[210:213], v151 offset:6144
	ds_read_b128 v[214:217], v151 offset:7168
	global_load_lds_dwordx4 v[146:147], off
	v_lshl_add_u64 v[146:147], s[58:59], 0, v[138:139]
	s_add_i32 m0, s27, 0xe000
	s_nop 0
	global_load_lds_dwordx4 v[146:147], off
	s_waitcnt vmcnt(8)
	s_waitcnt lgkmcnt(0)
	s_barrier
	s_setprio 1
	v_mfma_f32_16x16x32_bf16 v[126:129], v[142:145], v[180:183], v[126:129]
	v_mfma_f32_16x16x32_bf16 v[122:125], v[156:159], v[180:183], v[122:125]
	v_mfma_f32_16x16x32_bf16 v[118:121], v[142:145], v[188:191], v[118:121]
	v_mfma_f32_16x16x32_bf16 v[110:113], v[156:159], v[188:191], v[110:113]
	v_mfma_f32_16x16x32_bf16 v[102:105], v[142:145], v[202:205], v[102:105]
	v_mfma_f32_16x16x32_bf16 v[94:97], v[156:159], v[202:205], v[94:97]
	v_mfma_f32_16x16x32_bf16 v[86:89], v[142:145], v[210:213], v[86:89]
	v_mfma_f32_16x16x32_bf16 v[78:81], v[156:159], v[210:213], v[78:81]
	v_mfma_f32_16x16x32_bf16 v[126:129], v[152:155], v[184:187], v[126:129]
	v_mfma_f32_16x16x32_bf16 v[122:125], v[160:163], v[184:187], v[122:125]
	v_mfma_f32_16x16x32_bf16 v[118:121], v[152:155], v[192:195], v[118:121]
	v_mfma_f32_16x16x32_bf16 v[110:113], v[160:163], v[192:195], v[110:113]
	v_mfma_f32_16x16x32_bf16 v[102:105], v[152:155], v[206:209], v[102:105]
	v_mfma_f32_16x16x32_bf16 v[94:97], v[160:163], v[206:209], v[94:97]
	v_mfma_f32_16x16x32_bf16 v[86:89], v[152:155], v[214:217], v[86:89]
	v_mfma_f32_16x16x32_bf16 v[78:81], v[160:163], v[214:217], v[78:81]
	s_setprio 0
	s_setprio 1
	v_mfma_f32_16x16x32_bf16 v[114:117], v[164:167], v[180:183], v[114:117]
	v_mfma_f32_16x16x32_bf16 v[106:109], v[172:175], v[180:183], v[106:109]
	v_mfma_f32_16x16x32_bf16 v[98:101], v[164:167], v[188:191], v[98:101]
	v_mfma_f32_16x16x32_bf16 v[90:93], v[172:175], v[188:191], v[90:93]
	v_mfma_f32_16x16x32_bf16 v[82:85], v[164:167], v[202:205], v[82:85]
	v_mfma_f32_16x16x32_bf16 v[74:77], v[172:175], v[202:205], v[74:77]
	v_mfma_f32_16x16x32_bf16 v[70:73], v[164:167], v[210:213], v[70:73]
	v_mfma_f32_16x16x32_bf16 v[66:69], v[172:175], v[210:213], v[66:69]
	v_mfma_f32_16x16x32_bf16 v[114:117], v[168:171], v[184:187], v[114:117]
	v_mfma_f32_16x16x32_bf16 v[106:109], v[176:179], v[184:187], v[106:109]
	v_mfma_f32_16x16x32_bf16 v[98:101], v[168:171], v[192:195], v[98:101]
	v_mfma_f32_16x16x32_bf16 v[90:93], v[176:179], v[192:195], v[90:93]
	v_mfma_f32_16x16x32_bf16 v[82:85], v[168:171], v[206:209], v[82:85]
	v_mfma_f32_16x16x32_bf16 v[74:77], v[176:179], v[206:209], v[74:77]
	v_mfma_f32_16x16x32_bf16 v[70:73], v[168:171], v[214:217], v[70:73]
	v_mfma_f32_16x16x32_bf16 v[66:69], v[176:179], v[214:217], v[66:69]
	s_barrier
	s_setprio 0
	s_add_i32 s1, s72, s26
	v_lshl_add_u64 v[146:147], s[8:9], 0, v[196:197]
	s_mov_b32 m0, s1
	ds_read_b128 v[180:183], v151 offset:16384
	ds_read_b128 v[184:187], v151 offset:17408
	ds_read_b128 v[188:191], v151 offset:18432
	ds_read_b128 v[192:195], v151 offset:19456
	ds_read_b128 v[202:205], v151 offset:20480
	ds_read_b128 v[206:209], v151 offset:21504
	ds_read_b128 v[210:213], v151 offset:22528
	ds_read_b128 v[214:217], v151 offset:23552
	global_load_lds_dwordx4 v[146:147], off
	s_add_i32 m0, s1, 0x2000
	s_add_u32 s72, s8, 0x80000
	v_lshl_add_u64 v[218:219], s[8:9], 0, v[130:131]
	s_addc_u32 s73, s9, 0
	s_add_i32 s0, s0, s26
	global_load_lds_dwordx4 v[218:219], off
	v_lshl_add_u64 v[220:221], s[72:73], 0, v[196:197]
	s_mov_b32 m0, s0
	v_lshl_add_u64 v[222:223], s[62:63], 0, v[132:133]
	global_load_lds_dwordx4 v[220:221], off
	v_lshl_add_u64 v[220:221], s[72:73], 0, v[130:131]
	s_add_i32 m0, s0, 0x2000
	s_nop 0
	global_load_lds_dwordx4 v[220:221], off
	v_lshl_add_u64 v[220:221], s[62:63], 0, v[134:135]
	s_mov_b32 m0, s27
	s_nop 0
	global_load_lds_dwordx4 v[220:221], off
	s_mov_b32 m0, s28
	s_nop 0
	global_load_lds_dwordx4 v[222:223], off
	s_waitcnt vmcnt(8)
	s_waitcnt lgkmcnt(0)
	s_barrier
	s_setprio 1
	v_mfma_f32_16x16x32_bf16 v[62:65], v[142:145], v[180:183], v[62:65]
	v_mfma_f32_16x16x32_bf16 v[58:61], v[156:159], v[180:183], v[58:61]
	v_mfma_f32_16x16x32_bf16 v[54:57], v[142:145], v[188:191], v[54:57]
	v_mfma_f32_16x16x32_bf16 v[46:49], v[156:159], v[188:191], v[46:49]
	v_mfma_f32_16x16x32_bf16 v[38:41], v[142:145], v[202:205], v[38:41]
	v_mfma_f32_16x16x32_bf16 v[30:33], v[156:159], v[202:205], v[30:33]
	v_mfma_f32_16x16x32_bf16 v[22:25], v[142:145], v[210:213], v[22:25]
	v_mfma_f32_16x16x32_bf16 v[14:17], v[156:159], v[210:213], v[14:17]
	v_mfma_f32_16x16x32_bf16 v[62:65], v[152:155], v[184:187], v[62:65]
	v_mfma_f32_16x16x32_bf16 v[58:61], v[160:163], v[184:187], v[58:61]
	v_mfma_f32_16x16x32_bf16 v[54:57], v[152:155], v[192:195], v[54:57]
	v_mfma_f32_16x16x32_bf16 v[46:49], v[160:163], v[192:195], v[46:49]
	v_mfma_f32_16x16x32_bf16 v[38:41], v[152:155], v[206:209], v[38:41]
	v_mfma_f32_16x16x32_bf16 v[30:33], v[160:163], v[206:209], v[30:33]
	v_mfma_f32_16x16x32_bf16 v[22:25], v[152:155], v[214:217], v[22:25]
	v_mfma_f32_16x16x32_bf16 v[14:17], v[160:163], v[214:217], v[14:17]
	s_setprio 0
	s_setprio 1
	v_mfma_f32_16x16x32_bf16 v[50:53], v[164:167], v[180:183], v[50:53]
	v_mfma_f32_16x16x32_bf16 v[42:45], v[172:175], v[180:183], v[42:45]
	v_mfma_f32_16x16x32_bf16 v[34:37], v[164:167], v[188:191], v[34:37]
	v_mfma_f32_16x16x32_bf16 v[26:29], v[172:175], v[188:191], v[26:29]
	v_mfma_f32_16x16x32_bf16 v[18:21], v[164:167], v[202:205], v[18:21]
	v_mfma_f32_16x16x32_bf16 v[10:13], v[172:175], v[202:205], v[10:13]
	v_mfma_f32_16x16x32_bf16 v[6:9], v[164:167], v[210:213], v[6:9]
	v_mfma_f32_16x16x32_bf16 v[2:5], v[172:175], v[210:213], v[2:5]
	v_mfma_f32_16x16x32_bf16 v[50:53], v[168:171], v[184:187], v[50:53]
	v_mfma_f32_16x16x32_bf16 v[42:45], v[176:179], v[184:187], v[42:45]
	v_mfma_f32_16x16x32_bf16 v[34:37], v[168:171], v[192:195], v[34:37]
	v_mfma_f32_16x16x32_bf16 v[26:29], v[176:179], v[192:195], v[26:29]
	v_mfma_f32_16x16x32_bf16 v[18:21], v[168:171], v[206:209], v[18:21]
	v_mfma_f32_16x16x32_bf16 v[10:13], v[176:179], v[206:209], v[10:13]
	v_mfma_f32_16x16x32_bf16 v[6:9], v[168:171], v[214:217], v[6:9]
	v_mfma_f32_16x16x32_bf16 v[2:5], v[176:179], v[214:217], v[2:5]
	s_barrier
	s_setprio 0
	s_add_i32 s0, 0, 0x18000
	s_add_i32 s1, 0, 0x1c000
	v_add_u32_e32 v160, s0, v149
	v_add_u32_e32 v176, s1, v149
	ds_read_b128 v[142:145], v160
	ds_read_b128 v[152:155], v160 offset:1024
	ds_read_b128 v[156:159], v160 offset:2048
	ds_read_b128 v[160:163], v160 offset:3072
	ds_read_b128 v[164:167], v176
	ds_read_b128 v[168:171], v176 offset:1024
	ds_read_b128 v[172:175], v176 offset:2048
	ds_read_b128 v[176:179], v176 offset:3072
	s_add_u32 s62, s62, 0x80000
	s_addc_u32 s63, s63, 0
	s_mov_b32 m0, s29
	v_lshl_add_u64 v[224:225], s[62:63], 0, v[134:135]
	ds_read_b128 v[180:183], v151 offset:32768
	ds_read_b128 v[184:187], v151 offset:33792
	ds_read_b128 v[188:191], v151 offset:34816
	ds_read_b128 v[192:195], v151 offset:35840
	ds_read_b128 v[202:205], v151 offset:36864
	ds_read_b128 v[206:209], v151 offset:37888
	ds_read_b128 v[210:213], v151 offset:38912
	ds_read_b128 v[214:217], v151 offset:39936
	global_load_lds_dwordx4 v[224:225], off
	v_lshl_add_u64 v[224:225], s[62:63], 0, v[132:133]
	s_mov_b32 m0, s30
	s_nop 0
	global_load_lds_dwordx4 v[224:225], off
	s_waitcnt vmcnt(8)
	s_waitcnt lgkmcnt(0)
	s_barrier
	s_setprio 1
	v_mfma_f32_16x16x32_bf16 v[126:129], v[142:145], v[180:183], v[126:129]
	v_mfma_f32_16x16x32_bf16 v[122:125], v[156:159], v[180:183], v[122:125]
	v_mfma_f32_16x16x32_bf16 v[118:121], v[142:145], v[188:191], v[118:121]
	v_mfma_f32_16x16x32_bf16 v[110:113], v[156:159], v[188:191], v[110:113]
	v_mfma_f32_16x16x32_bf16 v[102:105], v[142:145], v[202:205], v[102:105]
	v_mfma_f32_16x16x32_bf16 v[94:97], v[156:159], v[202:205], v[94:97]
	v_mfma_f32_16x16x32_bf16 v[86:89], v[142:145], v[210:213], v[86:89]
	v_mfma_f32_16x16x32_bf16 v[78:81], v[156:159], v[210:213], v[78:81]
	v_mfma_f32_16x16x32_bf16 v[126:129], v[152:155], v[184:187], v[126:129]
	v_mfma_f32_16x16x32_bf16 v[122:125], v[160:163], v[184:187], v[122:125]
	v_mfma_f32_16x16x32_bf16 v[118:121], v[152:155], v[192:195], v[118:121]
	v_mfma_f32_16x16x32_bf16 v[110:113], v[160:163], v[192:195], v[110:113]
	v_mfma_f32_16x16x32_bf16 v[102:105], v[152:155], v[206:209], v[102:105]
	v_mfma_f32_16x16x32_bf16 v[94:97], v[160:163], v[206:209], v[94:97]
	v_mfma_f32_16x16x32_bf16 v[86:89], v[152:155], v[214:217], v[86:89]
	v_mfma_f32_16x16x32_bf16 v[78:81], v[160:163], v[214:217], v[78:81]
	s_setprio 0
	s_setprio 1
	v_mfma_f32_16x16x32_bf16 v[114:117], v[164:167], v[180:183], v[114:117]
	v_mfma_f32_16x16x32_bf16 v[106:109], v[172:175], v[180:183], v[106:109]
	v_mfma_f32_16x16x32_bf16 v[98:101], v[164:167], v[188:191], v[98:101]
	v_mfma_f32_16x16x32_bf16 v[90:93], v[172:175], v[188:191], v[90:93]
	v_mfma_f32_16x16x32_bf16 v[82:85], v[164:167], v[202:205], v[82:85]
	v_mfma_f32_16x16x32_bf16 v[74:77], v[172:175], v[202:205], v[74:77]
	v_mfma_f32_16x16x32_bf16 v[70:73], v[164:167], v[210:213], v[70:73]
	v_mfma_f32_16x16x32_bf16 v[66:69], v[172:175], v[210:213], v[66:69]
	v_mfma_f32_16x16x32_bf16 v[114:117], v[168:171], v[184:187], v[114:117]
	v_mfma_f32_16x16x32_bf16 v[106:109], v[176:179], v[184:187], v[106:109]
	v_mfma_f32_16x16x32_bf16 v[98:101], v[168:171], v[192:195], v[98:101]
	v_mfma_f32_16x16x32_bf16 v[90:93], v[176:179], v[192:195], v[90:93]
	v_mfma_f32_16x16x32_bf16 v[82:85], v[168:171], v[206:209], v[82:85]
	v_mfma_f32_16x16x32_bf16 v[74:77], v[176:179], v[206:209], v[74:77]
	v_mfma_f32_16x16x32_bf16 v[70:73], v[168:171], v[214:217], v[70:73]
	v_mfma_f32_16x16x32_bf16 v[66:69], v[176:179], v[214:217], v[66:69]
	s_barrier
	s_setprio 0
	s_add_i32 s0, s0, s26
	v_lshl_add_u64 v[146:147], v[146:147], 0, s[16:17]
	s_mov_b32 m0, s0
	ds_read_b128 v[180:183], v151 offset:49152
	ds_read_b128 v[184:187], v151 offset:50176
	ds_read_b128 v[188:191], v151 offset:51200
	ds_read_b128 v[192:195], v151 offset:52224
	ds_read_b128 v[202:205], v151 offset:53248
	ds_read_b128 v[206:209], v151 offset:54272
	ds_read_b128 v[210:213], v151 offset:55296
	ds_read_b128 v[214:217], v151 offset:56320
	global_load_lds_dwordx4 v[146:147], off
	s_add_i32 m0, s0, 0x2000
	s_add_u32 s8, s8, 0x80080
	v_lshl_add_u64 v[146:147], v[218:219], 0, s[16:17]
	s_addc_u32 s9, s9, 0
	s_add_i32 s0, s1, s26
	global_load_lds_dwordx4 v[146:147], off
	v_lshl_add_u64 v[146:147], s[8:9], 0, v[196:197]
	s_mov_b32 m0, s0
	s_nop 0
	global_load_lds_dwordx4 v[146:147], off
	v_lshl_add_u64 v[146:147], s[8:9], 0, v[130:131]
	s_add_i32 m0, s0, 0x2000
	s_nop 0
	global_load_lds_dwordx4 v[146:147], off
	v_lshl_add_u64 v[146:147], v[220:221], 0, s[16:17]
	s_mov_b32 m0, s31
	s_nop 0
	global_load_lds_dwordx4 v[146:147], off
	v_lshl_add_u64 v[146:147], v[222:223], 0, s[16:17]
	s_mov_b32 m0, s34
	s_nop 0
	global_load_lds_dwordx4 v[146:147], off
	s_waitcnt vmcnt(8)
	s_waitcnt lgkmcnt(0)
	s_barrier
	s_setprio 1
	v_mfma_f32_16x16x32_bf16 v[62:65], v[142:145], v[180:183], v[62:65]
	v_mfma_f32_16x16x32_bf16 v[58:61], v[156:159], v[180:183], v[58:61]
	v_mfma_f32_16x16x32_bf16 v[54:57], v[142:145], v[188:191], v[54:57]
	v_mfma_f32_16x16x32_bf16 v[46:49], v[156:159], v[188:191], v[46:49]
	v_mfma_f32_16x16x32_bf16 v[38:41], v[142:145], v[202:205], v[38:41]
	v_mfma_f32_16x16x32_bf16 v[30:33], v[156:159], v[202:205], v[30:33]
	v_mfma_f32_16x16x32_bf16 v[22:25], v[142:145], v[210:213], v[22:25]
	v_mfma_f32_16x16x32_bf16 v[14:17], v[156:159], v[210:213], v[14:17]
	v_mfma_f32_16x16x32_bf16 v[62:65], v[152:155], v[184:187], v[62:65]
	v_mfma_f32_16x16x32_bf16 v[58:61], v[160:163], v[184:187], v[58:61]
	v_mfma_f32_16x16x32_bf16 v[54:57], v[152:155], v[192:195], v[54:57]
	v_mfma_f32_16x16x32_bf16 v[46:49], v[160:163], v[192:195], v[46:49]
	v_mfma_f32_16x16x32_bf16 v[38:41], v[152:155], v[206:209], v[38:41]
	v_mfma_f32_16x16x32_bf16 v[30:33], v[160:163], v[206:209], v[30:33]
	v_mfma_f32_16x16x32_bf16 v[22:25], v[152:155], v[214:217], v[22:25]
	v_mfma_f32_16x16x32_bf16 v[14:17], v[160:163], v[214:217], v[14:17]
	s_setprio 0
	s_setprio 1
	v_mfma_f32_16x16x32_bf16 v[50:53], v[164:167], v[180:183], v[50:53]
	v_mfma_f32_16x16x32_bf16 v[42:45], v[172:175], v[180:183], v[42:45]
	v_mfma_f32_16x16x32_bf16 v[34:37], v[164:167], v[188:191], v[34:37]
	v_mfma_f32_16x16x32_bf16 v[26:29], v[172:175], v[188:191], v[26:29]
	v_mfma_f32_16x16x32_bf16 v[18:21], v[164:167], v[202:205], v[18:21]
	v_mfma_f32_16x16x32_bf16 v[10:13], v[172:175], v[202:205], v[10:13]
	v_mfma_f32_16x16x32_bf16 v[6:9], v[164:167], v[210:213], v[6:9]
	v_mfma_f32_16x16x32_bf16 v[2:5], v[172:175], v[210:213], v[2:5]
	v_mfma_f32_16x16x32_bf16 v[50:53], v[168:171], v[184:187], v[50:53]
	v_mfma_f32_16x16x32_bf16 v[42:45], v[176:179], v[184:187], v[42:45]
	v_mfma_f32_16x16x32_bf16 v[34:37], v[168:171], v[192:195], v[34:37]
	v_mfma_f32_16x16x32_bf16 v[26:29], v[176:179], v[192:195], v[26:29]
	v_mfma_f32_16x16x32_bf16 v[18:21], v[168:171], v[206:209], v[18:21]
	v_mfma_f32_16x16x32_bf16 v[10:13], v[176:179], v[206:209], v[10:13]
	v_mfma_f32_16x16x32_bf16 v[6:9], v[168:171], v[214:217], v[6:9]
	v_mfma_f32_16x16x32_bf16 v[2:5], v[176:179], v[214:217], v[2:5]
	s_barrier
	s_setprio 0
	s_add_u32 s69, s69, 0x100
	s_addc_u32 s70, s70, 0
	s_add_u32 s58, s58, 0x100
	s_addc_u32 s59, s59, 0
	s_cmp_ge_i32 s71, s64
	s_mov_b32 s8, s71
	s_cbranch_scc0 .LBB0_1135
	s_and_b64 vcc, exec, s[38:39]
	s_cbranch_vccz .LBB0_1138
	s_barrier

.LBB0_2239:
	s_add_i32 s73, s8, 2
	s_add_u32 s0, s44, 0xfff00080
	s_addc_u32 s1, s45, -1
	s_add_i32 s77, 0, 0x10000
	s_cmp_eq_u32 s70, s8
	s_cselect_b32 s67, s51, s1
	s_cselect_b32 s66, s53, s0
	s_cselect_b32 s9, s49, s72
	s_cselect_b32 s8, s69, s71
	s_add_i32 s78, 0, 0x14000
	v_add_u32_e32 v142, s77, v244
	v_add_u32_e32 v158, s78, v244
	ds_read_b128 v[130:133], v142
	ds_read_b128 v[134:137], v142 offset:1024
	ds_read_b128 v[138:141], v142 offset:2048
	ds_read_b128 v[142:145], v142 offset:3072
	ds_read_b128 v[146:149], v158
	ds_read_b128 v[150:153], v158 offset:1024
	ds_read_b128 v[154:157], v158 offset:2048
	ds_read_b128 v[158:161], v158 offset:3072
	v_lshl_add_u64 v[194:195], s[44:45], 0, v[210:211]
	s_add_i32 m0, s3, 0xc000
	ds_read_b128 v[162:165], v246
	ds_read_b128 v[166:169], v246 offset:1024
	ds_read_b128 v[170:173], v246 offset:2048
	ds_read_b128 v[174:177], v246 offset:3072
	ds_read_b128 v[178:181], v246 offset:4096
	ds_read_b128 v[182:185], v246 offset:5120
	ds_read_b128 v[186:189], v246 offset:6144
	ds_read_b128 v[190:193], v246 offset:7168
	global_load_lds_dwordx4 v[194:195], off
	v_lshl_add_u64 v[194:195], s[44:45], 0, v[208:209]
	s_add_i32 m0, s3, 0xe000
	s_nop 0
	global_load_lds_dwordx4 v[194:195], off
	s_waitcnt vmcnt(8)
	s_waitcnt lgkmcnt(0)
	s_barrier
	s_setprio 1
	v_mfma_f32_16x16x32_bf16 v[126:129], v[130:133], v[162:165], v[126:129]
	v_mfma_f32_16x16x32_bf16 v[122:125], v[138:141], v[162:165], v[122:125]
	v_mfma_f32_16x16x32_bf16 v[110:113], v[130:133], v[170:173], v[110:113]
	v_mfma_f32_16x16x32_bf16 v[106:109], v[138:141], v[170:173], v[106:109]
	v_mfma_f32_16x16x32_bf16 v[94:97], v[130:133], v[178:181], v[94:97]
	v_mfma_f32_16x16x32_bf16 v[90:93], v[138:141], v[178:181], v[90:93]
	v_mfma_f32_16x16x32_bf16 v[78:81], v[130:133], v[186:189], v[78:81]
	v_mfma_f32_16x16x32_bf16 v[74:77], v[138:141], v[186:189], v[74:77]
	v_mfma_f32_16x16x32_bf16 v[126:129], v[134:137], v[166:169], v[126:129]
	v_mfma_f32_16x16x32_bf16 v[122:125], v[142:145], v[166:169], v[122:125]
	v_mfma_f32_16x16x32_bf16 v[110:113], v[134:137], v[174:177], v[110:113]
	v_mfma_f32_16x16x32_bf16 v[106:109], v[142:145], v[174:177], v[106:109]
	v_mfma_f32_16x16x32_bf16 v[94:97], v[134:137], v[182:185], v[94:97]
	v_mfma_f32_16x16x32_bf16 v[90:93], v[142:145], v[182:185], v[90:93]
	v_mfma_f32_16x16x32_bf16 v[78:81], v[134:137], v[190:193], v[78:81]
	v_mfma_f32_16x16x32_bf16 v[74:77], v[142:145], v[190:193], v[74:77]
	s_setprio 0
	s_setprio 1
	v_mfma_f32_16x16x32_bf16 v[118:121], v[146:149], v[162:165], v[118:121]
	v_mfma_f32_16x16x32_bf16 v[114:117], v[154:157], v[162:165], v[114:117]
	v_mfma_f32_16x16x32_bf16 v[102:105], v[146:149], v[170:173], v[102:105]
	v_mfma_f32_16x16x32_bf16 v[98:101], v[154:157], v[170:173], v[98:101]
	v_mfma_f32_16x16x32_bf16 v[86:89], v[146:149], v[178:181], v[86:89]
	v_mfma_f32_16x16x32_bf16 v[82:85], v[154:157], v[178:181], v[82:85]
	v_mfma_f32_16x16x32_bf16 v[70:73], v[146:149], v[186:189], v[70:73]
	v_mfma_f32_16x16x32_bf16 v[66:69], v[154:157], v[186:189], v[66:69]
	v_mfma_f32_16x16x32_bf16 v[118:121], v[150:153], v[166:169], v[118:121]
	v_mfma_f32_16x16x32_bf16 v[114:117], v[158:161], v[166:169], v[114:117]
	v_mfma_f32_16x16x32_bf16 v[102:105], v[150:153], v[174:177], v[102:105]
	v_mfma_f32_16x16x32_bf16 v[98:101], v[158:161], v[174:177], v[98:101]
	v_mfma_f32_16x16x32_bf16 v[86:89], v[150:153], v[182:185], v[86:89]
	v_mfma_f32_16x16x32_bf16 v[82:85], v[158:161], v[182:185], v[82:85]
	v_mfma_f32_16x16x32_bf16 v[70:73], v[150:153], v[190:193], v[70:73]
	v_mfma_f32_16x16x32_bf16 v[66:69], v[158:161], v[190:193], v[66:69]
	s_barrier
	s_setprio 0
	s_add_i32 s0, s77, s2
	v_lshl_add_u64 v[194:195], s[8:9], 0, v[196:197]
	s_mov_b32 m0, s0
	ds_read_b128 v[162:165], v246 offset:16384
	ds_read_b128 v[166:169], v246 offset:17408
	ds_read_b128 v[170:173], v246 offset:18432
	ds_read_b128 v[174:177], v246 offset:19456
	ds_read_b128 v[178:181], v246 offset:20480
	ds_read_b128 v[182:185], v246 offset:21504
	ds_read_b128 v[186:189], v246 offset:22528
	ds_read_b128 v[190:193], v246 offset:23552
	global_load_lds_dwordx4 v[194:195], off
	s_add_i32 m0, s0, 0x2000
	s_add_u32 s0, s8, 0x100000
	v_lshl_add_u64 v[212:213], s[8:9], 0, v[202:203]
	s_addc_u32 s1, s9, 0
	s_add_i32 s77, s78, s2
	global_load_lds_dwordx4 v[212:213], off
	v_lshl_add_u64 v[214:215], s[0:1], 0, v[196:197]
	s_mov_b32 m0, s77
	v_lshl_add_u64 v[216:217], s[66:67], 0, v[204:205]
	global_load_lds_dwordx4 v[214:215], off
	v_lshl_add_u64 v[214:215], s[0:1], 0, v[202:203]
	s_add_i32 m0, s77, 0x2000
	s_nop 0
	global_load_lds_dwordx4 v[214:215], off
	v_lshl_add_u64 v[214:215], s[66:67], 0, v[206:207]
	s_mov_b32 m0, s3
	s_nop 0
	global_load_lds_dwordx4 v[214:215], off
	s_mov_b32 m0, s10
	s_nop 0
	global_load_lds_dwordx4 v[216:217], off
	s_waitcnt vmcnt(8)
	s_waitcnt lgkmcnt(0)
	s_barrier
	s_setprio 1
	v_mfma_f32_16x16x32_bf16 v[62:65], v[130:133], v[162:165], v[62:65]
	v_mfma_f32_16x16x32_bf16 v[58:61], v[138:141], v[162:165], v[58:61]
	v_mfma_f32_16x16x32_bf16 v[46:49], v[130:133], v[170:173], v[46:49]
	v_mfma_f32_16x16x32_bf16 v[42:45], v[138:141], v[170:173], v[42:45]
	v_mfma_f32_16x16x32_bf16 v[30:33], v[130:133], v[178:181], v[30:33]
	v_mfma_f32_16x16x32_bf16 v[26:29], v[138:141], v[178:181], v[26:29]
	v_mfma_f32_16x16x32_bf16 v[14:17], v[130:133], v[186:189], v[14:17]
	v_mfma_f32_16x16x32_bf16 v[10:13], v[138:141], v[186:189], v[10:13]
	v_mfma_f32_16x16x32_bf16 v[62:65], v[134:137], v[166:169], v[62:65]
	v_mfma_f32_16x16x32_bf16 v[58:61], v[142:145], v[166:169], v[58:61]
	v_mfma_f32_16x16x32_bf16 v[46:49], v[134:137], v[174:177], v[46:49]
	v_mfma_f32_16x16x32_bf16 v[42:45], v[142:145], v[174:177], v[42:45]
	v_mfma_f32_16x16x32_bf16 v[30:33], v[134:137], v[182:185], v[30:33]
	v_mfma_f32_16x16x32_bf16 v[26:29], v[142:145], v[182:185], v[26:29]
	v_mfma_f32_16x16x32_bf16 v[14:17], v[134:137], v[190:193], v[14:17]
	v_mfma_f32_16x16x32_bf16 v[10:13], v[142:145], v[190:193], v[10:13]
	s_setprio 0
	s_setprio 1
	v_mfma_f32_16x16x32_bf16 v[54:57], v[146:149], v[162:165], v[54:57]
	v_mfma_f32_16x16x32_bf16 v[50:53], v[154:157], v[162:165], v[50:53]
	v_mfma_f32_16x16x32_bf16 v[38:41], v[146:149], v[170:173], v[38:41]
	v_mfma_f32_16x16x32_bf16 v[34:37], v[154:157], v[170:173], v[34:37]
	v_mfma_f32_16x16x32_bf16 v[22:25], v[146:149], v[178:181], v[22:25]
	v_mfma_f32_16x16x32_bf16 v[18:21], v[154:157], v[178:181], v[18:21]
	v_mfma_f32_16x16x32_bf16 v[6:9], v[146:149], v[186:189], v[6:9]
	v_mfma_f32_16x16x32_bf16 v[2:5], v[154:157], v[186:189], v[2:5]
	v_mfma_f32_16x16x32_bf16 v[54:57], v[150:153], v[166:169], v[54:57]
	v_mfma_f32_16x16x32_bf16 v[50:53], v[158:161], v[166:169], v[50:53]
	v_mfma_f32_16x16x32_bf16 v[38:41], v[150:153], v[174:177], v[38:41]
	v_mfma_f32_16x16x32_bf16 v[34:37], v[158:161], v[174:177], v[34:37]
	v_mfma_f32_16x16x32_bf16 v[22:25], v[150:153], v[182:185], v[22:25]
	v_mfma_f32_16x16x32_bf16 v[18:21], v[158:161], v[182:185], v[18:21]
	v_mfma_f32_16x16x32_bf16 v[6:9], v[150:153], v[190:193], v[6:9]
	v_mfma_f32_16x16x32_bf16 v[2:5], v[158:161], v[190:193], v[2:5]
	s_barrier
	s_setprio 0
	s_add_i32 s77, 0, 0x18000
	s_add_i32 s78, 0, 0x1c000
	v_add_u32_e32 v142, s77, v244
	v_add_u32_e32 v158, s78, v244
	ds_read_b128 v[130:133], v142
	ds_read_b128 v[134:137], v142 offset:1024
	ds_read_b128 v[138:141], v142 offset:2048
	ds_read_b128 v[142:145], v142 offset:3072
	ds_read_b128 v[146:149], v158
	ds_read_b128 v[150:153], v158 offset:1024
	ds_read_b128 v[154:157], v158 offset:2048
	ds_read_b128 v[158:161], v158 offset:3072
	s_add_u32 s0, s66, 0x100000
	s_addc_u32 s1, s67, 0
	s_mov_b32 m0, s11
	v_lshl_add_u64 v[218:219], s[0:1], 0, v[206:207]
	ds_read_b128 v[162:165], v246 offset:32768
	ds_read_b128 v[166:169], v246 offset:33792
	ds_read_b128 v[170:173], v246 offset:34816
	ds_read_b128 v[174:177], v246 offset:35840
	ds_read_b128 v[178:181], v246 offset:36864
	ds_read_b128 v[182:185], v246 offset:37888
	ds_read_b128 v[186:189], v246 offset:38912
	ds_read_b128 v[190:193], v246 offset:39936
	global_load_lds_dwordx4 v[218:219], off
	v_lshl_add_u64 v[218:219], s[0:1], 0, v[204:205]
	s_mov_b32 m0, s26
	s_nop 0
	global_load_lds_dwordx4 v[218:219], off
	s_waitcnt vmcnt(8)
	s_waitcnt lgkmcnt(0)
	s_barrier
	s_setprio 1
	v_mfma_f32_16x16x32_bf16 v[126:129], v[130:133], v[162:165], v[126:129]
	v_mfma_f32_16x16x32_bf16 v[122:125], v[138:141], v[162:165], v[122:125]
	v_mfma_f32_16x16x32_bf16 v[110:113], v[130:133], v[170:173], v[110:113]
	v_mfma_f32_16x16x32_bf16 v[106:109], v[138:141], v[170:173], v[106:109]
	v_mfma_f32_16x16x32_bf16 v[94:97], v[130:133], v[178:181], v[94:97]
	v_mfma_f32_16x16x32_bf16 v[90:93], v[138:141], v[178:181], v[90:93]
	v_mfma_f32_16x16x32_bf16 v[78:81], v[130:133], v[186:189], v[78:81]
	v_mfma_f32_16x16x32_bf16 v[74:77], v[138:141], v[186:189], v[74:77]
	v_mfma_f32_16x16x32_bf16 v[126:129], v[134:137], v[166:169], v[126:129]
	v_mfma_f32_16x16x32_bf16 v[122:125], v[142:145], v[166:169], v[122:125]
	v_mfma_f32_16x16x32_bf16 v[110:113], v[134:137], v[174:177], v[110:113]
	v_mfma_f32_16x16x32_bf16 v[106:109], v[142:145], v[174:177], v[106:109]
	v_mfma_f32_16x16x32_bf16 v[94:97], v[134:137], v[182:185], v[94:97]
	v_mfma_f32_16x16x32_bf16 v[90:93], v[142:145], v[182:185], v[90:93]
	v_mfma_f32_16x16x32_bf16 v[78:81], v[134:137], v[190:193], v[78:81]
	v_mfma_f32_16x16x32_bf16 v[74:77], v[142:145], v[190:193], v[74:77]
	s_setprio 0
	s_setprio 1
	v_mfma_f32_16x16x32_bf16 v[118:121], v[146:149], v[162:165], v[118:121]
	v_mfma_f32_16x16x32_bf16 v[114:117], v[154:157], v[162:165], v[114:117]
	v_mfma_f32_16x16x32_bf16 v[102:105], v[146:149], v[170:173], v[102:105]
	v_mfma_f32_16x16x32_bf16 v[98:101], v[154:157], v[170:173], v[98:101]
	v_mfma_f32_16x16x32_bf16 v[86:89], v[146:149], v[178:181], v[86:89]
	v_mfma_f32_16x16x32_bf16 v[82:85], v[154:157], v[178:181], v[82:85]
	v_mfma_f32_16x16x32_bf16 v[70:73], v[146:149], v[186:189], v[70:73]
	v_mfma_f32_16x16x32_bf16 v[66:69], v[154:157], v[186:189], v[66:69]
	v_mfma_f32_16x16x32_bf16 v[118:121], v[150:153], v[166:169], v[118:121]
	v_mfma_f32_16x16x32_bf16 v[114:117], v[158:161], v[166:169], v[114:117]
	v_mfma_f32_16x16x32_bf16 v[102:105], v[150:153], v[174:177], v[102:105]
	v_mfma_f32_16x16x32_bf16 v[98:101], v[158:161], v[174:177], v[98:101]
	v_mfma_f32_16x16x32_bf16 v[86:89], v[150:153], v[182:185], v[86:89]
	v_mfma_f32_16x16x32_bf16 v[82:85], v[158:161], v[182:185], v[82:85]
	v_mfma_f32_16x16x32_bf16 v[70:73], v[150:153], v[190:193], v[70:73]
	v_mfma_f32_16x16x32_bf16 v[66:69], v[158:161], v[190:193], v[66:69]
	s_barrier
	s_setprio 0
	s_add_i32 s0, s77, s2
	v_lshl_add_u64 v[194:195], v[194:195], 0, s[16:17]
	s_mov_b32 m0, s0
	ds_read_b128 v[162:165], v246 offset:49152
	ds_read_b128 v[166:169], v246 offset:50176
	ds_read_b128 v[170:173], v246 offset:51200
	ds_read_b128 v[174:177], v246 offset:52224
	ds_read_b128 v[178:181], v246 offset:53248
	ds_read_b128 v[182:185], v246 offset:54272
	ds_read_b128 v[186:189], v246 offset:55296
	ds_read_b128 v[190:193], v246 offset:56320
	global_load_lds_dwordx4 v[194:195], off
	s_add_i32 m0, s0, 0x2000
	s_add_u32 s0, s8, 0x100080
	v_lshl_add_u64 v[194:195], v[212:213], 0, s[16:17]
	s_addc_u32 s1, s9, 0
	s_add_i32 s8, s78, s2
	global_load_lds_dwordx4 v[194:195], off
	v_lshl_add_u64 v[194:195], s[0:1], 0, v[196:197]
	s_mov_b32 m0, s8
	s_nop 0
	global_load_lds_dwordx4 v[194:195], off
	v_lshl_add_u64 v[194:195], s[0:1], 0, v[202:203]
	s_add_i32 m0, s8, 0x2000
	s_nop 0
	global_load_lds_dwordx4 v[194:195], off
	v_lshl_add_u64 v[194:195], v[214:215], 0, s[16:17]
	s_mov_b32 m0, s27
	s_nop 0
	global_load_lds_dwordx4 v[194:195], off
	v_lshl_add_u64 v[194:195], v[216:217], 0, s[16:17]
	s_mov_b32 m0, s28
	s_nop 0
	global_load_lds_dwordx4 v[194:195], off
	s_waitcnt vmcnt(8)
	s_waitcnt lgkmcnt(0)
	s_barrier
	s_setprio 1
	v_mfma_f32_16x16x32_bf16 v[62:65], v[130:133], v[162:165], v[62:65]
	v_mfma_f32_16x16x32_bf16 v[58:61], v[138:141], v[162:165], v[58:61]
	v_mfma_f32_16x16x32_bf16 v[46:49], v[130:133], v[170:173], v[46:49]
	v_mfma_f32_16x16x32_bf16 v[42:45], v[138:141], v[170:173], v[42:45]
	v_mfma_f32_16x16x32_bf16 v[30:33], v[130:133], v[178:181], v[30:33]
	v_mfma_f32_16x16x32_bf16 v[26:29], v[138:141], v[178:181], v[26:29]
	v_mfma_f32_16x16x32_bf16 v[14:17], v[130:133], v[186:189], v[14:17]
	v_mfma_f32_16x16x32_bf16 v[10:13], v[138:141], v[186:189], v[10:13]
	v_mfma_f32_16x16x32_bf16 v[62:65], v[134:137], v[166:169], v[62:65]
	v_mfma_f32_16x16x32_bf16 v[58:61], v[142:145], v[166:169], v[58:61]
	v_mfma_f32_16x16x32_bf16 v[46:49], v[134:137], v[174:177], v[46:49]
	v_mfma_f32_16x16x32_bf16 v[42:45], v[142:145], v[174:177], v[42:45]
	v_mfma_f32_16x16x32_bf16 v[30:33], v[134:137], v[182:185], v[30:33]
	v_mfma_f32_16x16x32_bf16 v[26:29], v[142:145], v[182:185], v[26:29]
	v_mfma_f32_16x16x32_bf16 v[14:17], v[134:137], v[190:193], v[14:17]
	v_mfma_f32_16x16x32_bf16 v[10:13], v[142:145], v[190:193], v[10:13]
	s_setprio 0
	s_setprio 1
	v_mfma_f32_16x16x32_bf16 v[54:57], v[146:149], v[162:165], v[54:57]
	v_mfma_f32_16x16x32_bf16 v[50:53], v[154:157], v[162:165], v[50:53]
	v_mfma_f32_16x16x32_bf16 v[38:41], v[146:149], v[170:173], v[38:41]
	v_mfma_f32_16x16x32_bf16 v[34:37], v[154:157], v[170:173], v[34:37]
	v_mfma_f32_16x16x32_bf16 v[22:25], v[146:149], v[178:181], v[22:25]
	v_mfma_f32_16x16x32_bf16 v[18:21], v[154:157], v[178:181], v[18:21]
	v_mfma_f32_16x16x32_bf16 v[6:9], v[146:149], v[186:189], v[6:9]
	v_mfma_f32_16x16x32_bf16 v[2:5], v[154:157], v[186:189], v[2:5]
	v_mfma_f32_16x16x32_bf16 v[54:57], v[150:153], v[166:169], v[54:57]
	v_mfma_f32_16x16x32_bf16 v[50:53], v[158:161], v[166:169], v[50:53]
	v_mfma_f32_16x16x32_bf16 v[38:41], v[150:153], v[174:177], v[38:41]
	v_mfma_f32_16x16x32_bf16 v[34:37], v[158:161], v[174:177], v[34:37]
	v_mfma_f32_16x16x32_bf16 v[22:25], v[150:153], v[182:185], v[22:25]
	v_mfma_f32_16x16x32_bf16 v[18:21], v[158:161], v[182:185], v[18:21]
	v_mfma_f32_16x16x32_bf16 v[6:9], v[150:153], v[190:193], v[6:9]
	v_mfma_f32_16x16x32_bf16 v[2:5], v[158:161], v[190:193], v[2:5]
	s_barrier
	s_setprio 0
	s_add_u32 s71, s71, 0x100
	s_addc_u32 s72, s72, 0
	s_add_u32 s44, s44, 0x100
	s_addc_u32 s45, s45, 0
	s_cmp_ge_i32 s73, s35
	s_mov_b32 s8, s73
	s_cbranch_scc0 .LBB0_2239
	s_and_b64 vcc, exec, s[46:47]
	s_cbranch_vccz .LBB0_2242
	s_barrier

.LBB0_2357:
	s_add_i32 s77, s8, 2
	s_add_u32 s0, s62, 0xfff80080
	s_addc_u32 s1, s63, -1
	s_add_i32 s78, 0, 0x10000
	s_cmp_eq_u32 s71, s8
	s_cselect_b32 s65, s41, s1
	s_cselect_b32 s64, s45, s0
	s_cselect_b32 s9, s43, s73
	s_cselect_b32 s8, s70, s72
	s_add_i32 s79, 0, 0x14000
	v_add_u32_e32 v142, s78, v188
	v_add_u32_e32 v158, s79, v188
	ds_read_b128 v[130:133], v142
	ds_read_b128 v[134:137], v142 offset:1024
	ds_read_b128 v[138:141], v142 offset:2048
	ds_read_b128 v[142:145], v142 offset:3072
	ds_read_b128 v[146:149], v158
	ds_read_b128 v[150:153], v158 offset:1024
	ds_read_b128 v[154:157], v158 offset:2048
	ds_read_b128 v[158:161], v158 offset:3072
	v_lshl_add_u64 v[194:195], s[62:63], 0, v[178:179]
	s_add_i32 m0, s27, 0xc000
	ds_read_b128 v[162:165], v189
	ds_read_b128 v[180:183], v189 offset:1024
	ds_read_b128 v[184:187], v189 offset:2048
	ds_read_b128 v[190:193], v189 offset:3072
	ds_read_b128 v[202:205], v189 offset:4096
	ds_read_b128 v[206:209], v189 offset:5120
	ds_read_b128 v[210:213], v189 offset:6144
	ds_read_b128 v[214:217], v189 offset:7168
	global_load_lds_dwordx4 v[194:195], off
	v_lshl_add_u64 v[194:195], s[62:63], 0, v[176:177]
	s_add_i32 m0, s27, 0xe000
	s_nop 0
	global_load_lds_dwordx4 v[194:195], off
	s_waitcnt vmcnt(8)
	s_waitcnt lgkmcnt(0)
	s_barrier
	s_setprio 1
	v_mfma_f32_16x16x32_bf16 v[126:129], v[130:133], v[162:165], v[126:129]
	v_mfma_f32_16x16x32_bf16 v[122:125], v[138:141], v[162:165], v[122:125]
	v_mfma_f32_16x16x32_bf16 v[110:113], v[130:133], v[184:187], v[110:113]
	v_mfma_f32_16x16x32_bf16 v[106:109], v[138:141], v[184:187], v[106:109]
	v_mfma_f32_16x16x32_bf16 v[98:101], v[130:133], v[202:205], v[98:101]
	v_mfma_f32_16x16x32_bf16 v[90:93], v[138:141], v[202:205], v[90:93]
	v_mfma_f32_16x16x32_bf16 v[82:85], v[130:133], v[210:213], v[82:85]
	v_mfma_f32_16x16x32_bf16 v[74:77], v[138:141], v[210:213], v[74:77]
	v_mfma_f32_16x16x32_bf16 v[126:129], v[134:137], v[180:183], v[126:129]
	v_mfma_f32_16x16x32_bf16 v[122:125], v[142:145], v[180:183], v[122:125]
	v_mfma_f32_16x16x32_bf16 v[110:113], v[134:137], v[190:193], v[110:113]
	v_mfma_f32_16x16x32_bf16 v[106:109], v[142:145], v[190:193], v[106:109]
	v_mfma_f32_16x16x32_bf16 v[98:101], v[134:137], v[206:209], v[98:101]
	v_mfma_f32_16x16x32_bf16 v[90:93], v[142:145], v[206:209], v[90:93]
	v_mfma_f32_16x16x32_bf16 v[82:85], v[134:137], v[214:217], v[82:85]
	v_mfma_f32_16x16x32_bf16 v[74:77], v[142:145], v[214:217], v[74:77]
	s_setprio 0
	s_setprio 1
	v_mfma_f32_16x16x32_bf16 v[118:121], v[146:149], v[162:165], v[118:121]
	v_mfma_f32_16x16x32_bf16 v[114:117], v[154:157], v[162:165], v[114:117]
	v_mfma_f32_16x16x32_bf16 v[102:105], v[146:149], v[184:187], v[102:105]
	v_mfma_f32_16x16x32_bf16 v[94:97], v[154:157], v[184:187], v[94:97]
	v_mfma_f32_16x16x32_bf16 v[86:89], v[146:149], v[202:205], v[86:89]
	v_mfma_f32_16x16x32_bf16 v[78:81], v[154:157], v[202:205], v[78:81]
	v_mfma_f32_16x16x32_bf16 v[70:73], v[146:149], v[210:213], v[70:73]
	v_mfma_f32_16x16x32_bf16 v[66:69], v[154:157], v[210:213], v[66:69]
	v_mfma_f32_16x16x32_bf16 v[118:121], v[150:153], v[180:183], v[118:121]
	v_mfma_f32_16x16x32_bf16 v[114:117], v[158:161], v[180:183], v[114:117]
	v_mfma_f32_16x16x32_bf16 v[102:105], v[150:153], v[190:193], v[102:105]
	v_mfma_f32_16x16x32_bf16 v[94:97], v[158:161], v[190:193], v[94:97]
	v_mfma_f32_16x16x32_bf16 v[86:89], v[150:153], v[206:209], v[86:89]
	v_mfma_f32_16x16x32_bf16 v[78:81], v[158:161], v[206:209], v[78:81]
	v_mfma_f32_16x16x32_bf16 v[70:73], v[150:153], v[214:217], v[70:73]
	v_mfma_f32_16x16x32_bf16 v[66:69], v[158:161], v[214:217], v[66:69]
	s_barrier
	s_setprio 0
	s_add_i32 s0, s78, s26
	v_lshl_add_u64 v[194:195], s[8:9], 0, v[196:197]
	s_mov_b32 m0, s0
	ds_read_b128 v[162:165], v189 offset:16384
	ds_read_b128 v[180:183], v189 offset:17408
	ds_read_b128 v[184:187], v189 offset:18432
	ds_read_b128 v[190:193], v189 offset:19456
	ds_read_b128 v[202:205], v189 offset:20480
	ds_read_b128 v[206:209], v189 offset:21504
	ds_read_b128 v[210:213], v189 offset:22528
	ds_read_b128 v[214:217], v189 offset:23552
	global_load_lds_dwordx4 v[194:195], off
	s_add_i32 m0, s0, 0x2000
	s_add_u32 s0, s8, 0x80000
	v_lshl_add_u64 v[218:219], s[8:9], 0, v[170:171]
	s_addc_u32 s1, s9, 0
	s_add_i32 s78, s79, s26
	global_load_lds_dwordx4 v[218:219], off
	v_lshl_add_u64 v[220:221], s[0:1], 0, v[196:197]
	s_mov_b32 m0, s78
	v_lshl_add_u64 v[222:223], s[64:65], 0, v[168:169]
	global_load_lds_dwordx4 v[220:221], off
	v_lshl_add_u64 v[220:221], s[0:1], 0, v[170:171]
	s_add_i32 m0, s78, 0x2000
	s_nop 0
	global_load_lds_dwordx4 v[220:221], off
	v_lshl_add_u64 v[220:221], s[64:65], 0, v[166:167]
	s_mov_b32 m0, s27
	s_nop 0
	global_load_lds_dwordx4 v[220:221], off
	s_mov_b32 m0, s28
	s_nop 0
	global_load_lds_dwordx4 v[222:223], off
	s_waitcnt vmcnt(8)
	s_waitcnt lgkmcnt(0)
	s_barrier
	s_setprio 1
	v_mfma_f32_16x16x32_bf16 v[62:65], v[130:133], v[162:165], v[62:65]
	v_mfma_f32_16x16x32_bf16 v[58:61], v[138:141], v[162:165], v[58:61]
	v_mfma_f32_16x16x32_bf16 v[50:53], v[130:133], v[184:187], v[50:53]
	v_mfma_f32_16x16x32_bf16 v[42:45], v[138:141], v[184:187], v[42:45]
	v_mfma_f32_16x16x32_bf16 v[34:37], v[130:133], v[202:205], v[34:37]
	v_mfma_f32_16x16x32_bf16 v[26:29], v[138:141], v[202:205], v[26:29]
	v_mfma_f32_16x16x32_bf16 v[18:21], v[130:133], v[210:213], v[18:21]
	v_mfma_f32_16x16x32_bf16 v[10:13], v[138:141], v[210:213], v[10:13]
	v_mfma_f32_16x16x32_bf16 v[62:65], v[134:137], v[180:183], v[62:65]
	v_mfma_f32_16x16x32_bf16 v[58:61], v[142:145], v[180:183], v[58:61]
	v_mfma_f32_16x16x32_bf16 v[50:53], v[134:137], v[190:193], v[50:53]
	v_mfma_f32_16x16x32_bf16 v[42:45], v[142:145], v[190:193], v[42:45]
	v_mfma_f32_16x16x32_bf16 v[34:37], v[134:137], v[206:209], v[34:37]
	v_mfma_f32_16x16x32_bf16 v[26:29], v[142:145], v[206:209], v[26:29]
	v_mfma_f32_16x16x32_bf16 v[18:21], v[134:137], v[214:217], v[18:21]
	v_mfma_f32_16x16x32_bf16 v[10:13], v[142:145], v[214:217], v[10:13]
	s_setprio 0
	s_setprio 1
	v_mfma_f32_16x16x32_bf16 v[54:57], v[146:149], v[162:165], v[54:57]
	v_mfma_f32_16x16x32_bf16 v[46:49], v[154:157], v[162:165], v[46:49]
	v_mfma_f32_16x16x32_bf16 v[38:41], v[146:149], v[184:187], v[38:41]
	v_mfma_f32_16x16x32_bf16 v[30:33], v[154:157], v[184:187], v[30:33]
	v_mfma_f32_16x16x32_bf16 v[22:25], v[146:149], v[202:205], v[22:25]
	v_mfma_f32_16x16x32_bf16 v[14:17], v[154:157], v[202:205], v[14:17]
	v_mfma_f32_16x16x32_bf16 v[6:9], v[146:149], v[210:213], v[6:9]
	v_mfma_f32_16x16x32_bf16 v[2:5], v[154:157], v[210:213], v[2:5]
	v_mfma_f32_16x16x32_bf16 v[54:57], v[150:153], v[180:183], v[54:57]
	v_mfma_f32_16x16x32_bf16 v[46:49], v[158:161], v[180:183], v[46:49]
	v_mfma_f32_16x16x32_bf16 v[38:41], v[150:153], v[190:193], v[38:41]
	v_mfma_f32_16x16x32_bf16 v[30:33], v[158:161], v[190:193], v[30:33]
	v_mfma_f32_16x16x32_bf16 v[22:25], v[150:153], v[206:209], v[22:25]
	v_mfma_f32_16x16x32_bf16 v[14:17], v[158:161], v[206:209], v[14:17]
	v_mfma_f32_16x16x32_bf16 v[6:9], v[150:153], v[214:217], v[6:9]
	v_mfma_f32_16x16x32_bf16 v[2:5], v[158:161], v[214:217], v[2:5]
	s_barrier
	s_setprio 0
	s_add_i32 s78, 0, 0x18000
	s_add_i32 s79, 0, 0x1c000
	v_add_u32_e32 v142, s78, v188
	v_add_u32_e32 v158, s79, v188
	ds_read_b128 v[130:133], v142
	ds_read_b128 v[134:137], v142 offset:1024
	ds_read_b128 v[138:141], v142 offset:2048
	ds_read_b128 v[142:145], v142 offset:3072
	ds_read_b128 v[146:149], v158
	ds_read_b128 v[150:153], v158 offset:1024
	ds_read_b128 v[154:157], v158 offset:2048
	ds_read_b128 v[158:161], v158 offset:3072
	s_add_u32 s0, s64, 0x80000
	s_addc_u32 s1, s65, 0
	s_mov_b32 m0, s29
	v_lshl_add_u64 v[224:225], s[0:1], 0, v[166:167]
	ds_read_b128 v[162:165], v189 offset:32768
	ds_read_b128 v[180:183], v189 offset:33792
	ds_read_b128 v[184:187], v189 offset:34816
	ds_read_b128 v[190:193], v189 offset:35840
	ds_read_b128 v[202:205], v189 offset:36864
	ds_read_b128 v[206:209], v189 offset:37888
	ds_read_b128 v[210:213], v189 offset:38912
	ds_read_b128 v[214:217], v189 offset:39936
	global_load_lds_dwordx4 v[224:225], off
	v_lshl_add_u64 v[224:225], s[0:1], 0, v[168:169]
	s_mov_b32 m0, s30
	s_nop 0
	global_load_lds_dwordx4 v[224:225], off
	s_waitcnt vmcnt(8)
	s_waitcnt lgkmcnt(0)
	s_barrier
	s_setprio 1
	v_mfma_f32_16x16x32_bf16 v[126:129], v[130:133], v[162:165], v[126:129]
	v_mfma_f32_16x16x32_bf16 v[122:125], v[138:141], v[162:165], v[122:125]
	v_mfma_f32_16x16x32_bf16 v[110:113], v[130:133], v[184:187], v[110:113]
	v_mfma_f32_16x16x32_bf16 v[106:109], v[138:141], v[184:187], v[106:109]
	v_mfma_f32_16x16x32_bf16 v[98:101], v[130:133], v[202:205], v[98:101]
	v_mfma_f32_16x16x32_bf16 v[90:93], v[138:141], v[202:205], v[90:93]
	v_mfma_f32_16x16x32_bf16 v[82:85], v[130:133], v[210:213], v[82:85]
	v_mfma_f32_16x16x32_bf16 v[74:77], v[138:141], v[210:213], v[74:77]
	v_mfma_f32_16x16x32_bf16 v[126:129], v[134:137], v[180:183], v[126:129]
	v_mfma_f32_16x16x32_bf16 v[122:125], v[142:145], v[180:183], v[122:125]
	v_mfma_f32_16x16x32_bf16 v[110:113], v[134:137], v[190:193], v[110:113]
	v_mfma_f32_16x16x32_bf16 v[106:109], v[142:145], v[190:193], v[106:109]
	v_mfma_f32_16x16x32_bf16 v[98:101], v[134:137], v[206:209], v[98:101]
	v_mfma_f32_16x16x32_bf16 v[90:93], v[142:145], v[206:209], v[90:93]
	v_mfma_f32_16x16x32_bf16 v[82:85], v[134:137], v[214:217], v[82:85]
	v_mfma_f32_16x16x32_bf16 v[74:77], v[142:145], v[214:217], v[74:77]
	s_setprio 0
	s_setprio 1
	v_mfma_f32_16x16x32_bf16 v[118:121], v[146:149], v[162:165], v[118:121]
	v_mfma_f32_16x16x32_bf16 v[114:117], v[154:157], v[162:165], v[114:117]
	v_mfma_f32_16x16x32_bf16 v[102:105], v[146:149], v[184:187], v[102:105]
	v_mfma_f32_16x16x32_bf16 v[94:97], v[154:157], v[184:187], v[94:97]
	v_mfma_f32_16x16x32_bf16 v[86:89], v[146:149], v[202:205], v[86:89]
	v_mfma_f32_16x16x32_bf16 v[78:81], v[154:157], v[202:205], v[78:81]
	v_mfma_f32_16x16x32_bf16 v[70:73], v[146:149], v[210:213], v[70:73]
	v_mfma_f32_16x16x32_bf16 v[66:69], v[154:157], v[210:213], v[66:69]
	v_mfma_f32_16x16x32_bf16 v[118:121], v[150:153], v[180:183], v[118:121]
	v_mfma_f32_16x16x32_bf16 v[114:117], v[158:161], v[180:183], v[114:117]
	v_mfma_f32_16x16x32_bf16 v[102:105], v[150:153], v[190:193], v[102:105]
	v_mfma_f32_16x16x32_bf16 v[94:97], v[158:161], v[190:193], v[94:97]
	v_mfma_f32_16x16x32_bf16 v[86:89], v[150:153], v[206:209], v[86:89]
	v_mfma_f32_16x16x32_bf16 v[78:81], v[158:161], v[206:209], v[78:81]
	v_mfma_f32_16x16x32_bf16 v[70:73], v[150:153], v[214:217], v[70:73]
	v_mfma_f32_16x16x32_bf16 v[66:69], v[158:161], v[214:217], v[66:69]
	s_barrier
	s_setprio 0
	s_add_i32 s0, s78, s26
	v_lshl_add_u64 v[194:195], v[194:195], 0, s[16:17]
	s_mov_b32 m0, s0
	ds_read_b128 v[162:165], v189 offset:49152
	ds_read_b128 v[180:183], v189 offset:50176
	ds_read_b128 v[184:187], v189 offset:51200
	ds_read_b128 v[190:193], v189 offset:52224
	ds_read_b128 v[202:205], v189 offset:53248
	ds_read_b128 v[206:209], v189 offset:54272
	ds_read_b128 v[210:213], v189 offset:55296
	ds_read_b128 v[214:217], v189 offset:56320
	global_load_lds_dwordx4 v[194:195], off
	s_add_i32 m0, s0, 0x2000
	s_add_u32 s0, s8, 0x80080
	v_lshl_add_u64 v[194:195], v[218:219], 0, s[16:17]
	s_addc_u32 s1, s9, 0
	s_add_i32 s8, s79, s26
	global_load_lds_dwordx4 v[194:195], off
	v_lshl_add_u64 v[194:195], s[0:1], 0, v[196:197]
	s_mov_b32 m0, s8
	s_nop 0
	global_load_lds_dwordx4 v[194:195], off
	v_lshl_add_u64 v[194:195], s[0:1], 0, v[170:171]
	s_add_i32 m0, s8, 0x2000
	s_nop 0
	global_load_lds_dwordx4 v[194:195], off
	v_lshl_add_u64 v[194:195], v[220:221], 0, s[16:17]
	s_mov_b32 m0, s35
	s_nop 0
	global_load_lds_dwordx4 v[194:195], off
	v_lshl_add_u64 v[194:195], v[222:223], 0, s[16:17]
	s_mov_b32 m0, s53
	s_nop 0
	global_load_lds_dwordx4 v[194:195], off
	s_waitcnt vmcnt(8)
	s_waitcnt lgkmcnt(0)
	s_barrier
	s_setprio 1
	v_mfma_f32_16x16x32_bf16 v[62:65], v[130:133], v[162:165], v[62:65]
	v_mfma_f32_16x16x32_bf16 v[58:61], v[138:141], v[162:165], v[58:61]
	v_mfma_f32_16x16x32_bf16 v[50:53], v[130:133], v[184:187], v[50:53]
	v_mfma_f32_16x16x32_bf16 v[42:45], v[138:141], v[184:187], v[42:45]
	v_mfma_f32_16x16x32_bf16 v[34:37], v[130:133], v[202:205], v[34:37]
	v_mfma_f32_16x16x32_bf16 v[26:29], v[138:141], v[202:205], v[26:29]
	v_mfma_f32_16x16x32_bf16 v[18:21], v[130:133], v[210:213], v[18:21]
	v_mfma_f32_16x16x32_bf16 v[10:13], v[138:141], v[210:213], v[10:13]
	v_mfma_f32_16x16x32_bf16 v[62:65], v[134:137], v[180:183], v[62:65]
	v_mfma_f32_16x16x32_bf16 v[58:61], v[142:145], v[180:183], v[58:61]
	v_mfma_f32_16x16x32_bf16 v[50:53], v[134:137], v[190:193], v[50:53]
	v_mfma_f32_16x16x32_bf16 v[42:45], v[142:145], v[190:193], v[42:45]
	v_mfma_f32_16x16x32_bf16 v[34:37], v[134:137], v[206:209], v[34:37]
	v_mfma_f32_16x16x32_bf16 v[26:29], v[142:145], v[206:209], v[26:29]
	v_mfma_f32_16x16x32_bf16 v[18:21], v[134:137], v[214:217], v[18:21]
	v_mfma_f32_16x16x32_bf16 v[10:13], v[142:145], v[214:217], v[10:13]
	s_setprio 0
	s_setprio 1
	v_mfma_f32_16x16x32_bf16 v[54:57], v[146:149], v[162:165], v[54:57]
	v_mfma_f32_16x16x32_bf16 v[46:49], v[154:157], v[162:165], v[46:49]
	v_mfma_f32_16x16x32_bf16 v[38:41], v[146:149], v[184:187], v[38:41]
	v_mfma_f32_16x16x32_bf16 v[30:33], v[154:157], v[184:187], v[30:33]
	v_mfma_f32_16x16x32_bf16 v[22:25], v[146:149], v[202:205], v[22:25]
	v_mfma_f32_16x16x32_bf16 v[14:17], v[154:157], v[202:205], v[14:17]
	v_mfma_f32_16x16x32_bf16 v[6:9], v[146:149], v[210:213], v[6:9]
	v_mfma_f32_16x16x32_bf16 v[2:5], v[154:157], v[210:213], v[2:5]
	v_mfma_f32_16x16x32_bf16 v[54:57], v[150:153], v[180:183], v[54:57]
	v_mfma_f32_16x16x32_bf16 v[46:49], v[158:161], v[180:183], v[46:49]
	v_mfma_f32_16x16x32_bf16 v[38:41], v[150:153], v[190:193], v[38:41]
	v_mfma_f32_16x16x32_bf16 v[30:33], v[158:161], v[190:193], v[30:33]
	v_mfma_f32_16x16x32_bf16 v[22:25], v[150:153], v[206:209], v[22:25]
	v_mfma_f32_16x16x32_bf16 v[14:17], v[158:161], v[206:209], v[14:17]
	v_mfma_f32_16x16x32_bf16 v[6:9], v[150:153], v[214:217], v[6:9]
	v_mfma_f32_16x16x32_bf16 v[2:5], v[158:161], v[214:217], v[2:5]
	s_barrier
	s_setprio 0
	s_add_u32 s72, s72, 0x100
	s_addc_u32 s73, s73, 0
	s_add_u32 s62, s62, 0x100
	s_addc_u32 s63, s63, 0
	s_cmp_ge_i32 s77, s69
	s_mov_b32 s8, s77
	s_cbranch_scc0 .LBB0_2357
	s_and_b64 vcc, exec, s[38:39]
	s_cbranch_vccz .LBB0_2360
	s_barrier

.LBB0_2507:
	s_add_i32 s69, s8, 2
	s_add_u32 s0, s52, 0xfff80080
	s_addc_u32 s1, s53, -1
	s_add_i32 s70, 0, 0x10000
	s_cmp_eq_u32 s66, s8
	s_cselect_b32 s59, s41, s1
	s_cselect_b32 s58, s45, s0
	s_cselect_b32 s9, s43, s68
	s_cselect_b32 s8, s65, s67
	s_add_i32 s71, 0, 0x14000
	v_add_u32_e32 v156, s70, v141
	v_add_u32_e32 v172, s71, v141
	ds_read_b128 v[144:147], v156
	ds_read_b128 v[148:151], v156 offset:1024
	ds_read_b128 v[152:155], v156 offset:2048
	ds_read_b128 v[156:159], v156 offset:3072
	ds_read_b128 v[160:163], v172
	ds_read_b128 v[164:167], v172 offset:1024
	ds_read_b128 v[168:171], v172 offset:2048
	ds_read_b128 v[172:175], v172 offset:3072
	v_lshl_add_u64 v[214:215], s[52:53], 0, v[138:139]
	s_add_i32 m0, s27, 0xc000
	ds_read_b128 v[176:179], v143
	ds_read_b128 v[180:183], v143 offset:1024
	ds_read_b128 v[184:187], v143 offset:2048
	ds_read_b128 v[188:191], v143 offset:3072
	ds_read_b128 v[192:195], v143 offset:4096
	ds_read_b128 v[202:205], v143 offset:5120
	ds_read_b128 v[206:209], v143 offset:6144
	ds_read_b128 v[210:213], v143 offset:7168
	global_load_lds_dwordx4 v[214:215], off
	v_lshl_add_u64 v[214:215], s[52:53], 0, v[136:137]
	s_add_i32 m0, s27, 0xe000
	s_nop 0
	global_load_lds_dwordx4 v[214:215], off
	s_waitcnt vmcnt(8)
	s_waitcnt lgkmcnt(0)
	s_barrier
	s_setprio 1
	v_mfma_f32_16x16x32_bf16 v[126:129], v[144:147], v[176:179], v[126:129]
	v_mfma_f32_16x16x32_bf16 v[118:121], v[152:155], v[176:179], v[118:121]
	v_mfma_f32_16x16x32_bf16 v[110:113], v[144:147], v[184:187], v[110:113]
	v_mfma_f32_16x16x32_bf16 v[102:105], v[152:155], v[184:187], v[102:105]
	v_mfma_f32_16x16x32_bf16 v[94:97], v[144:147], v[192:195], v[94:97]
	v_mfma_f32_16x16x32_bf16 v[86:89], v[152:155], v[192:195], v[86:89]
	v_mfma_f32_16x16x32_bf16 v[78:81], v[144:147], v[206:209], v[78:81]
	v_mfma_f32_16x16x32_bf16 v[70:73], v[152:155], v[206:209], v[70:73]
	v_mfma_f32_16x16x32_bf16 v[126:129], v[148:151], v[180:183], v[126:129]
	v_mfma_f32_16x16x32_bf16 v[118:121], v[156:159], v[180:183], v[118:121]
	v_mfma_f32_16x16x32_bf16 v[110:113], v[148:151], v[188:191], v[110:113]
	v_mfma_f32_16x16x32_bf16 v[102:105], v[156:159], v[188:191], v[102:105]
	v_mfma_f32_16x16x32_bf16 v[94:97], v[148:151], v[202:205], v[94:97]
	v_mfma_f32_16x16x32_bf16 v[86:89], v[156:159], v[202:205], v[86:89]
	v_mfma_f32_16x16x32_bf16 v[78:81], v[148:151], v[210:213], v[78:81]
	v_mfma_f32_16x16x32_bf16 v[70:73], v[156:159], v[210:213], v[70:73]
	s_setprio 0
	s_setprio 1
	v_mfma_f32_16x16x32_bf16 v[122:125], v[160:163], v[176:179], v[122:125]
	v_mfma_f32_16x16x32_bf16 v[114:117], v[168:171], v[176:179], v[114:117]
	v_mfma_f32_16x16x32_bf16 v[106:109], v[160:163], v[184:187], v[106:109]
	v_mfma_f32_16x16x32_bf16 v[98:101], v[168:171], v[184:187], v[98:101]
	v_mfma_f32_16x16x32_bf16 v[90:93], v[160:163], v[192:195], v[90:93]
	v_mfma_f32_16x16x32_bf16 v[82:85], v[168:171], v[192:195], v[82:85]
	v_mfma_f32_16x16x32_bf16 v[74:77], v[160:163], v[206:209], v[74:77]
	v_mfma_f32_16x16x32_bf16 v[66:69], v[168:171], v[206:209], v[66:69]
	v_mfma_f32_16x16x32_bf16 v[122:125], v[164:167], v[180:183], v[122:125]
	v_mfma_f32_16x16x32_bf16 v[114:117], v[172:175], v[180:183], v[114:117]
	v_mfma_f32_16x16x32_bf16 v[106:109], v[164:167], v[188:191], v[106:109]
	v_mfma_f32_16x16x32_bf16 v[98:101], v[172:175], v[188:191], v[98:101]
	v_mfma_f32_16x16x32_bf16 v[90:93], v[164:167], v[202:205], v[90:93]
	v_mfma_f32_16x16x32_bf16 v[82:85], v[172:175], v[202:205], v[82:85]
	v_mfma_f32_16x16x32_bf16 v[74:77], v[164:167], v[210:213], v[74:77]
	v_mfma_f32_16x16x32_bf16 v[66:69], v[172:175], v[210:213], v[66:69]
	s_barrier
	s_setprio 0
	s_add_i32 s0, s70, s26
	v_lshl_add_u64 v[214:215], s[8:9], 0, v[196:197]
	s_mov_b32 m0, s0
	ds_read_b128 v[176:179], v143 offset:16384
	ds_read_b128 v[180:183], v143 offset:17408
	ds_read_b128 v[184:187], v143 offset:18432
	ds_read_b128 v[188:191], v143 offset:19456
	ds_read_b128 v[192:195], v143 offset:20480
	ds_read_b128 v[202:205], v143 offset:21504
	ds_read_b128 v[206:209], v143 offset:22528
	ds_read_b128 v[210:213], v143 offset:23552
	global_load_lds_dwordx4 v[214:215], off
	s_add_i32 m0, s0, 0x2000
	s_add_u32 s0, s8, 0x80000
	v_lshl_add_u64 v[216:217], s[8:9], 0, v[130:131]
	s_addc_u32 s1, s9, 0
	s_add_i32 s70, s71, s26
	global_load_lds_dwordx4 v[216:217], off
	v_lshl_add_u64 v[218:219], s[0:1], 0, v[196:197]
	s_mov_b32 m0, s70
	v_lshl_add_u64 v[220:221], s[58:59], 0, v[132:133]
	global_load_lds_dwordx4 v[218:219], off
	v_lshl_add_u64 v[218:219], s[0:1], 0, v[130:131]
	s_add_i32 m0, s70, 0x2000
	s_nop 0
	global_load_lds_dwordx4 v[218:219], off
	v_lshl_add_u64 v[218:219], s[58:59], 0, v[134:135]
	s_mov_b32 m0, s27
	s_nop 0
	global_load_lds_dwordx4 v[218:219], off
	s_mov_b32 m0, s28
	s_nop 0
	global_load_lds_dwordx4 v[220:221], off
	s_waitcnt vmcnt(8)
	s_waitcnt lgkmcnt(0)
	s_barrier
	s_setprio 1
	v_mfma_f32_16x16x32_bf16 v[62:65], v[144:147], v[176:179], v[62:65]
	v_mfma_f32_16x16x32_bf16 v[54:57], v[152:155], v[176:179], v[54:57]
	v_mfma_f32_16x16x32_bf16 v[46:49], v[144:147], v[184:187], v[46:49]
	v_mfma_f32_16x16x32_bf16 v[38:41], v[152:155], v[184:187], v[38:41]
	v_mfma_f32_16x16x32_bf16 v[30:33], v[144:147], v[192:195], v[30:33]
	v_mfma_f32_16x16x32_bf16 v[22:25], v[152:155], v[192:195], v[22:25]
	v_mfma_f32_16x16x32_bf16 v[14:17], v[144:147], v[206:209], v[14:17]
	v_mfma_f32_16x16x32_bf16 v[6:9], v[152:155], v[206:209], v[6:9]
	v_mfma_f32_16x16x32_bf16 v[62:65], v[148:151], v[180:183], v[62:65]
	v_mfma_f32_16x16x32_bf16 v[54:57], v[156:159], v[180:183], v[54:57]
	v_mfma_f32_16x16x32_bf16 v[46:49], v[148:151], v[188:191], v[46:49]
	v_mfma_f32_16x16x32_bf16 v[38:41], v[156:159], v[188:191], v[38:41]
	v_mfma_f32_16x16x32_bf16 v[30:33], v[148:151], v[202:205], v[30:33]
	v_mfma_f32_16x16x32_bf16 v[22:25], v[156:159], v[202:205], v[22:25]
	v_mfma_f32_16x16x32_bf16 v[14:17], v[148:151], v[210:213], v[14:17]
	v_mfma_f32_16x16x32_bf16 v[6:9], v[156:159], v[210:213], v[6:9]
	s_setprio 0
	s_setprio 1
	v_mfma_f32_16x16x32_bf16 v[58:61], v[160:163], v[176:179], v[58:61]
	v_mfma_f32_16x16x32_bf16 v[50:53], v[168:171], v[176:179], v[50:53]
	v_mfma_f32_16x16x32_bf16 v[42:45], v[160:163], v[184:187], v[42:45]
	v_mfma_f32_16x16x32_bf16 v[34:37], v[168:171], v[184:187], v[34:37]
	v_mfma_f32_16x16x32_bf16 v[26:29], v[160:163], v[192:195], v[26:29]
	v_mfma_f32_16x16x32_bf16 v[18:21], v[168:171], v[192:195], v[18:21]
	v_mfma_f32_16x16x32_bf16 v[10:13], v[160:163], v[206:209], v[10:13]
	v_mfma_f32_16x16x32_bf16 v[2:5], v[168:171], v[206:209], v[2:5]
	v_mfma_f32_16x16x32_bf16 v[58:61], v[164:167], v[180:183], v[58:61]
	v_mfma_f32_16x16x32_bf16 v[50:53], v[172:175], v[180:183], v[50:53]
	v_mfma_f32_16x16x32_bf16 v[42:45], v[164:167], v[188:191], v[42:45]
	v_mfma_f32_16x16x32_bf16 v[34:37], v[172:175], v[188:191], v[34:37]
	v_mfma_f32_16x16x32_bf16 v[26:29], v[164:167], v[202:205], v[26:29]
	v_mfma_f32_16x16x32_bf16 v[18:21], v[172:175], v[202:205], v[18:21]
	v_mfma_f32_16x16x32_bf16 v[10:13], v[164:167], v[210:213], v[10:13]
	v_mfma_f32_16x16x32_bf16 v[2:5], v[172:175], v[210:213], v[2:5]
	s_barrier
	s_setprio 0
	s_add_i32 s70, 0, 0x18000
	s_add_i32 s71, 0, 0x1c000
	v_add_u32_e32 v156, s70, v141
	v_add_u32_e32 v172, s71, v141
	ds_read_b128 v[144:147], v156
	ds_read_b128 v[148:151], v156 offset:1024
	ds_read_b128 v[152:155], v156 offset:2048
	ds_read_b128 v[156:159], v156 offset:3072
	ds_read_b128 v[160:163], v172
	ds_read_b128 v[164:167], v172 offset:1024
	ds_read_b128 v[168:171], v172 offset:2048
	ds_read_b128 v[172:175], v172 offset:3072
	s_add_u32 s0, s58, 0x80000
	s_addc_u32 s1, s59, 0
	s_mov_b32 m0, s29
	v_lshl_add_u64 v[222:223], s[0:1], 0, v[134:135]
	ds_read_b128 v[176:179], v143 offset:32768
	ds_read_b128 v[180:183], v143 offset:33792
	ds_read_b128 v[184:187], v143 offset:34816
	ds_read_b128 v[188:191], v143 offset:35840
	ds_read_b128 v[192:195], v143 offset:36864
	ds_read_b128 v[202:205], v143 offset:37888
	ds_read_b128 v[206:209], v143 offset:38912
	ds_read_b128 v[210:213], v143 offset:39936
	global_load_lds_dwordx4 v[222:223], off
	v_lshl_add_u64 v[222:223], s[0:1], 0, v[132:133]
	s_mov_b32 m0, s30
	s_nop 0
	global_load_lds_dwordx4 v[222:223], off
	s_waitcnt vmcnt(8)
	s_waitcnt lgkmcnt(0)
	s_barrier
	s_setprio 1
	v_mfma_f32_16x16x32_bf16 v[126:129], v[144:147], v[176:179], v[126:129]
	v_mfma_f32_16x16x32_bf16 v[118:121], v[152:155], v[176:179], v[118:121]
	v_mfma_f32_16x16x32_bf16 v[110:113], v[144:147], v[184:187], v[110:113]
	v_mfma_f32_16x16x32_bf16 v[102:105], v[152:155], v[184:187], v[102:105]
	v_mfma_f32_16x16x32_bf16 v[94:97], v[144:147], v[192:195], v[94:97]
	v_mfma_f32_16x16x32_bf16 v[86:89], v[152:155], v[192:195], v[86:89]
	v_mfma_f32_16x16x32_bf16 v[78:81], v[144:147], v[206:209], v[78:81]
	v_mfma_f32_16x16x32_bf16 v[70:73], v[152:155], v[206:209], v[70:73]
	v_mfma_f32_16x16x32_bf16 v[126:129], v[148:151], v[180:183], v[126:129]
	v_mfma_f32_16x16x32_bf16 v[118:121], v[156:159], v[180:183], v[118:121]
	v_mfma_f32_16x16x32_bf16 v[110:113], v[148:151], v[188:191], v[110:113]
	v_mfma_f32_16x16x32_bf16 v[102:105], v[156:159], v[188:191], v[102:105]
	v_mfma_f32_16x16x32_bf16 v[94:97], v[148:151], v[202:205], v[94:97]
	v_mfma_f32_16x16x32_bf16 v[86:89], v[156:159], v[202:205], v[86:89]
	v_mfma_f32_16x16x32_bf16 v[78:81], v[148:151], v[210:213], v[78:81]
	v_mfma_f32_16x16x32_bf16 v[70:73], v[156:159], v[210:213], v[70:73]
	s_setprio 0
	s_setprio 1
	v_mfma_f32_16x16x32_bf16 v[122:125], v[160:163], v[176:179], v[122:125]
	v_mfma_f32_16x16x32_bf16 v[114:117], v[168:171], v[176:179], v[114:117]
	v_mfma_f32_16x16x32_bf16 v[106:109], v[160:163], v[184:187], v[106:109]
	v_mfma_f32_16x16x32_bf16 v[98:101], v[168:171], v[184:187], v[98:101]
	v_mfma_f32_16x16x32_bf16 v[90:93], v[160:163], v[192:195], v[90:93]
	v_mfma_f32_16x16x32_bf16 v[82:85], v[168:171], v[192:195], v[82:85]
	v_mfma_f32_16x16x32_bf16 v[74:77], v[160:163], v[206:209], v[74:77]
	v_mfma_f32_16x16x32_bf16 v[66:69], v[168:171], v[206:209], v[66:69]
	v_mfma_f32_16x16x32_bf16 v[122:125], v[164:167], v[180:183], v[122:125]
	v_mfma_f32_16x16x32_bf16 v[114:117], v[172:175], v[180:183], v[114:117]
	v_mfma_f32_16x16x32_bf16 v[106:109], v[164:167], v[188:191], v[106:109]
	v_mfma_f32_16x16x32_bf16 v[98:101], v[172:175], v[188:191], v[98:101]
	v_mfma_f32_16x16x32_bf16 v[90:93], v[164:167], v[202:205], v[90:93]
	v_mfma_f32_16x16x32_bf16 v[82:85], v[172:175], v[202:205], v[82:85]
	v_mfma_f32_16x16x32_bf16 v[74:77], v[164:167], v[210:213], v[74:77]
	v_mfma_f32_16x16x32_bf16 v[66:69], v[172:175], v[210:213], v[66:69]
	s_barrier
	s_setprio 0
	s_add_i32 s0, s70, s26
	v_lshl_add_u64 v[214:215], v[214:215], 0, s[16:17]
	s_mov_b32 m0, s0
	ds_read_b128 v[176:179], v143 offset:49152
	ds_read_b128 v[180:183], v143 offset:50176
	ds_read_b128 v[184:187], v143 offset:51200
	ds_read_b128 v[188:191], v143 offset:52224
	ds_read_b128 v[192:195], v143 offset:53248
	ds_read_b128 v[202:205], v143 offset:54272
	ds_read_b128 v[206:209], v143 offset:55296
	ds_read_b128 v[210:213], v143 offset:56320
	global_load_lds_dwordx4 v[214:215], off
	s_add_i32 m0, s0, 0x2000
	s_add_u32 s0, s8, 0x80080
	v_lshl_add_u64 v[214:215], v[216:217], 0, s[16:17]
	s_addc_u32 s1, s9, 0
	s_add_i32 s8, s71, s26
	global_load_lds_dwordx4 v[214:215], off
	v_lshl_add_u64 v[214:215], s[0:1], 0, v[196:197]
	s_mov_b32 m0, s8
	s_nop 0
	global_load_lds_dwordx4 v[214:215], off
	v_lshl_add_u64 v[214:215], s[0:1], 0, v[130:131]
	s_add_i32 m0, s8, 0x2000
	s_nop 0
	global_load_lds_dwordx4 v[214:215], off
	v_lshl_add_u64 v[214:215], v[218:219], 0, s[16:17]
	s_mov_b32 m0, s31
	s_nop 0
	global_load_lds_dwordx4 v[214:215], off
	v_lshl_add_u64 v[214:215], v[220:221], 0, s[16:17]
	s_mov_b32 m0, s34
	s_nop 0
	global_load_lds_dwordx4 v[214:215], off
	s_waitcnt vmcnt(8)
	s_waitcnt lgkmcnt(0)
	s_barrier
	s_setprio 1
	v_mfma_f32_16x16x32_bf16 v[62:65], v[144:147], v[176:179], v[62:65]
	v_mfma_f32_16x16x32_bf16 v[54:57], v[152:155], v[176:179], v[54:57]
	v_mfma_f32_16x16x32_bf16 v[46:49], v[144:147], v[184:187], v[46:49]
	v_mfma_f32_16x16x32_bf16 v[38:41], v[152:155], v[184:187], v[38:41]
	v_mfma_f32_16x16x32_bf16 v[30:33], v[144:147], v[192:195], v[30:33]
	v_mfma_f32_16x16x32_bf16 v[22:25], v[152:155], v[192:195], v[22:25]
	v_mfma_f32_16x16x32_bf16 v[14:17], v[144:147], v[206:209], v[14:17]
	v_mfma_f32_16x16x32_bf16 v[6:9], v[152:155], v[206:209], v[6:9]
	v_mfma_f32_16x16x32_bf16 v[62:65], v[148:151], v[180:183], v[62:65]
	v_mfma_f32_16x16x32_bf16 v[54:57], v[156:159], v[180:183], v[54:57]
	v_mfma_f32_16x16x32_bf16 v[46:49], v[148:151], v[188:191], v[46:49]
	v_mfma_f32_16x16x32_bf16 v[38:41], v[156:159], v[188:191], v[38:41]
	v_mfma_f32_16x16x32_bf16 v[30:33], v[148:151], v[202:205], v[30:33]
	v_mfma_f32_16x16x32_bf16 v[22:25], v[156:159], v[202:205], v[22:25]
	v_mfma_f32_16x16x32_bf16 v[14:17], v[148:151], v[210:213], v[14:17]
	v_mfma_f32_16x16x32_bf16 v[6:9], v[156:159], v[210:213], v[6:9]
	s_setprio 0
	s_setprio 1
	v_mfma_f32_16x16x32_bf16 v[58:61], v[160:163], v[176:179], v[58:61]
	v_mfma_f32_16x16x32_bf16 v[50:53], v[168:171], v[176:179], v[50:53]
	v_mfma_f32_16x16x32_bf16 v[42:45], v[160:163], v[184:187], v[42:45]
	v_mfma_f32_16x16x32_bf16 v[34:37], v[168:171], v[184:187], v[34:37]
	v_mfma_f32_16x16x32_bf16 v[26:29], v[160:163], v[192:195], v[26:29]
	v_mfma_f32_16x16x32_bf16 v[18:21], v[168:171], v[192:195], v[18:21]
	v_mfma_f32_16x16x32_bf16 v[10:13], v[160:163], v[206:209], v[10:13]
	v_mfma_f32_16x16x32_bf16 v[2:5], v[168:171], v[206:209], v[2:5]
	v_mfma_f32_16x16x32_bf16 v[58:61], v[164:167], v[180:183], v[58:61]
	v_mfma_f32_16x16x32_bf16 v[50:53], v[172:175], v[180:183], v[50:53]
	v_mfma_f32_16x16x32_bf16 v[42:45], v[164:167], v[188:191], v[42:45]
	v_mfma_f32_16x16x32_bf16 v[34:37], v[172:175], v[188:191], v[34:37]
	v_mfma_f32_16x16x32_bf16 v[26:29], v[164:167], v[202:205], v[26:29]
	v_mfma_f32_16x16x32_bf16 v[18:21], v[172:175], v[202:205], v[18:21]
	v_mfma_f32_16x16x32_bf16 v[10:13], v[164:167], v[210:213], v[10:13]
	v_mfma_f32_16x16x32_bf16 v[2:5], v[172:175], v[210:213], v[2:5]
	s_barrier
	s_setprio 0
	s_add_u32 s67, s67, 0x100
	s_addc_u32 s68, s68, 0
	s_add_u32 s52, s52, 0x100
	s_addc_u32 s53, s53, 0
	s_cmp_ge_i32 s69, s62
	s_mov_b32 s8, s69
	s_cbranch_scc0 .LBB0_2507
	s_and_b64 vcc, exec, s[38:39]
	s_cbranch_vccz .LBB0_2510
	s_barrier

.LBB0_2588:
	s_add_i32 s72, s48, 2
	s_add_u32 s8, s46, 0x100
	s_addc_u32 s9, s47, 0
	s_add_i32 s0, 0, 0x10000
	s_cmp_eq_u32 s41, s48
	s_cselect_b32 s51, s43, s9
	s_cselect_b32 s50, s42, s8
	s_cselect_b32 s49, s45, s71
	s_cselect_b32 s48, s44, s70
	s_add_i32 s73, 0, 0x14000
	v_add_u32_e32 v142, s0, v188
	v_add_u32_e32 v172, s73, v188
	ds_read_b128 v[130:133], v142
	ds_read_b128 v[134:137], v142 offset:1024
	ds_read_b128 v[138:141], v142 offset:2048
	ds_read_b128 v[142:145], v142 offset:3072
	ds_read_b128 v[146:149], v172
	ds_read_b128 v[164:167], v172 offset:1024
	ds_read_b128 v[168:171], v172 offset:2048
	ds_read_b128 v[172:175], v172 offset:3072
	v_lshl_add_u64 v[194:195], s[46:47], 0, v[162:163]
	s_add_i32 m0, s27, 0xc000
	ds_read_b128 v[176:179], v189
	ds_read_b128 v[180:183], v189 offset:1024
	ds_read_b128 v[184:187], v189 offset:2048
	ds_read_b128 v[190:193], v189 offset:3072
	ds_read_b128 v[202:205], v189 offset:4096
	ds_read_b128 v[206:209], v189 offset:5120
	ds_read_b128 v[210:213], v189 offset:6144
	ds_read_b128 v[214:217], v189 offset:7168
	global_load_lds_dwordx4 v[194:195], off
	v_lshl_add_u64 v[194:195], s[46:47], 0, v[160:161]
	s_add_i32 m0, s27, 0xe000
	s_nop 0
	global_load_lds_dwordx4 v[194:195], off
	s_waitcnt vmcnt(8)
	s_waitcnt lgkmcnt(0)
	s_barrier
	s_setprio 1
	v_mfma_f32_16x16x32_bf16 v[126:129], v[130:133], v[176:179], v[126:129]
	v_mfma_f32_16x16x32_bf16 v[122:125], v[138:141], v[176:179], v[122:125]
	v_mfma_f32_16x16x32_bf16 v[110:113], v[130:133], v[184:187], v[110:113]
	v_mfma_f32_16x16x32_bf16 v[106:109], v[138:141], v[184:187], v[106:109]
	v_mfma_f32_16x16x32_bf16 v[98:101], v[130:133], v[202:205], v[98:101]
	v_mfma_f32_16x16x32_bf16 v[90:93], v[138:141], v[202:205], v[90:93]
	v_mfma_f32_16x16x32_bf16 v[82:85], v[130:133], v[210:213], v[82:85]
	v_mfma_f32_16x16x32_bf16 v[74:77], v[138:141], v[210:213], v[74:77]
	v_mfma_f32_16x16x32_bf16 v[126:129], v[134:137], v[180:183], v[126:129]
	v_mfma_f32_16x16x32_bf16 v[122:125], v[142:145], v[180:183], v[122:125]
	v_mfma_f32_16x16x32_bf16 v[110:113], v[134:137], v[190:193], v[110:113]
	v_mfma_f32_16x16x32_bf16 v[106:109], v[142:145], v[190:193], v[106:109]
	v_mfma_f32_16x16x32_bf16 v[98:101], v[134:137], v[206:209], v[98:101]
	v_mfma_f32_16x16x32_bf16 v[90:93], v[142:145], v[206:209], v[90:93]
	v_mfma_f32_16x16x32_bf16 v[82:85], v[134:137], v[214:217], v[82:85]
	v_mfma_f32_16x16x32_bf16 v[74:77], v[142:145], v[214:217], v[74:77]
	s_setprio 0
	s_setprio 1
	v_mfma_f32_16x16x32_bf16 v[118:121], v[146:149], v[176:179], v[118:121]
	v_mfma_f32_16x16x32_bf16 v[114:117], v[168:171], v[176:179], v[114:117]
	v_mfma_f32_16x16x32_bf16 v[102:105], v[146:149], v[184:187], v[102:105]
	v_mfma_f32_16x16x32_bf16 v[94:97], v[168:171], v[184:187], v[94:97]
	v_mfma_f32_16x16x32_bf16 v[86:89], v[146:149], v[202:205], v[86:89]
	v_mfma_f32_16x16x32_bf16 v[78:81], v[168:171], v[202:205], v[78:81]
	v_mfma_f32_16x16x32_bf16 v[70:73], v[146:149], v[210:213], v[70:73]
	v_mfma_f32_16x16x32_bf16 v[66:69], v[168:171], v[210:213], v[66:69]
	v_mfma_f32_16x16x32_bf16 v[118:121], v[164:167], v[180:183], v[118:121]
	v_mfma_f32_16x16x32_bf16 v[114:117], v[172:175], v[180:183], v[114:117]
	v_mfma_f32_16x16x32_bf16 v[102:105], v[164:167], v[190:193], v[102:105]
	v_mfma_f32_16x16x32_bf16 v[94:97], v[172:175], v[190:193], v[94:97]
	v_mfma_f32_16x16x32_bf16 v[86:89], v[164:167], v[206:209], v[86:89]
	v_mfma_f32_16x16x32_bf16 v[78:81], v[172:175], v[206:209], v[78:81]
	v_mfma_f32_16x16x32_bf16 v[70:73], v[164:167], v[214:217], v[70:73]
	v_mfma_f32_16x16x32_bf16 v[66:69], v[172:175], v[214:217], v[66:69]
	s_barrier
	s_setprio 0
	s_add_i32 s0, s0, s26
	v_lshl_add_u64 v[194:195], s[48:49], 0, v[196:197]
	s_mov_b32 m0, s0
	ds_read_b128 v[176:179], v189 offset:16384
	ds_read_b128 v[180:183], v189 offset:17408
	ds_read_b128 v[184:187], v189 offset:18432
	ds_read_b128 v[190:193], v189 offset:19456
	ds_read_b128 v[202:205], v189 offset:20480
	ds_read_b128 v[206:209], v189 offset:21504
	ds_read_b128 v[210:213], v189 offset:22528
	ds_read_b128 v[214:217], v189 offset:23552
	global_load_lds_dwordx4 v[194:195], off
	s_add_i32 m0, s0, 0x2000
	s_add_u32 s0, s48, 0x158000
	v_lshl_add_u64 v[218:219], s[48:49], 0, v[154:155]
	s_addc_u32 s1, s49, 0
	s_add_i32 s46, s73, s26
	global_load_lds_dwordx4 v[218:219], off
	v_lshl_add_u64 v[220:221], s[0:1], 0, v[196:197]
	s_mov_b32 m0, s46
	v_lshl_add_u64 v[222:223], s[50:51], 0, v[152:153]
	global_load_lds_dwordx4 v[220:221], off
	v_lshl_add_u64 v[220:221], s[0:1], 0, v[154:155]
	s_add_i32 m0, s46, 0x2000
	s_nop 0
	global_load_lds_dwordx4 v[220:221], off
	v_lshl_add_u64 v[220:221], s[50:51], 0, v[150:151]
	s_mov_b32 m0, s27
	s_nop 0
	global_load_lds_dwordx4 v[220:221], off
	s_mov_b32 m0, s30
	s_nop 0
	global_load_lds_dwordx4 v[222:223], off
	s_waitcnt vmcnt(8)
	s_waitcnt lgkmcnt(0)
	s_barrier
	s_setprio 1
	v_mfma_f32_16x16x32_bf16 v[62:65], v[130:133], v[176:179], v[62:65]
	v_mfma_f32_16x16x32_bf16 v[58:61], v[138:141], v[176:179], v[58:61]
	v_mfma_f32_16x16x32_bf16 v[50:53], v[130:133], v[184:187], v[50:53]
	v_mfma_f32_16x16x32_bf16 v[42:45], v[138:141], v[184:187], v[42:45]
	v_mfma_f32_16x16x32_bf16 v[34:37], v[130:133], v[202:205], v[34:37]
	v_mfma_f32_16x16x32_bf16 v[26:29], v[138:141], v[202:205], v[26:29]
	v_mfma_f32_16x16x32_bf16 v[18:21], v[130:133], v[210:213], v[18:21]
	v_mfma_f32_16x16x32_bf16 v[10:13], v[138:141], v[210:213], v[10:13]
	v_mfma_f32_16x16x32_bf16 v[62:65], v[134:137], v[180:183], v[62:65]
	v_mfma_f32_16x16x32_bf16 v[58:61], v[142:145], v[180:183], v[58:61]
	v_mfma_f32_16x16x32_bf16 v[50:53], v[134:137], v[190:193], v[50:53]
	v_mfma_f32_16x16x32_bf16 v[42:45], v[142:145], v[190:193], v[42:45]
	v_mfma_f32_16x16x32_bf16 v[34:37], v[134:137], v[206:209], v[34:37]
	v_mfma_f32_16x16x32_bf16 v[26:29], v[142:145], v[206:209], v[26:29]
	v_mfma_f32_16x16x32_bf16 v[18:21], v[134:137], v[214:217], v[18:21]
	v_mfma_f32_16x16x32_bf16 v[10:13], v[142:145], v[214:217], v[10:13]
	s_setprio 0
	s_setprio 1
	v_mfma_f32_16x16x32_bf16 v[54:57], v[146:149], v[176:179], v[54:57]
	v_mfma_f32_16x16x32_bf16 v[46:49], v[168:171], v[176:179], v[46:49]
	v_mfma_f32_16x16x32_bf16 v[38:41], v[146:149], v[184:187], v[38:41]
	v_mfma_f32_16x16x32_bf16 v[30:33], v[168:171], v[184:187], v[30:33]
	v_mfma_f32_16x16x32_bf16 v[22:25], v[146:149], v[202:205], v[22:25]
	v_mfma_f32_16x16x32_bf16 v[14:17], v[168:171], v[202:205], v[14:17]
	v_mfma_f32_16x16x32_bf16 v[6:9], v[146:149], v[210:213], v[6:9]
	v_mfma_f32_16x16x32_bf16 v[2:5], v[168:171], v[210:213], v[2:5]
	v_mfma_f32_16x16x32_bf16 v[54:57], v[164:167], v[180:183], v[54:57]
	v_mfma_f32_16x16x32_bf16 v[46:49], v[172:175], v[180:183], v[46:49]
	v_mfma_f32_16x16x32_bf16 v[38:41], v[164:167], v[190:193], v[38:41]
	v_mfma_f32_16x16x32_bf16 v[30:33], v[172:175], v[190:193], v[30:33]
	v_mfma_f32_16x16x32_bf16 v[22:25], v[164:167], v[206:209], v[22:25]
	v_mfma_f32_16x16x32_bf16 v[14:17], v[172:175], v[206:209], v[14:17]
	v_mfma_f32_16x16x32_bf16 v[6:9], v[164:167], v[214:217], v[6:9]
	v_mfma_f32_16x16x32_bf16 v[2:5], v[172:175], v[214:217], v[2:5]
	s_barrier
	s_setprio 0
	s_add_i32 s46, 0, 0x18000
	s_add_i32 s47, 0, 0x1c000
	v_add_u32_e32 v142, s46, v188
	v_add_u32_e32 v172, s47, v188
	ds_read_b128 v[130:133], v142
	ds_read_b128 v[134:137], v142 offset:1024
	ds_read_b128 v[138:141], v142 offset:2048
	ds_read_b128 v[142:145], v142 offset:3072
	ds_read_b128 v[146:149], v172
	ds_read_b128 v[164:167], v172 offset:1024
	ds_read_b128 v[168:171], v172 offset:2048
	ds_read_b128 v[172:175], v172 offset:3072
	s_add_u32 s0, s50, 0x158000
	s_addc_u32 s1, s51, 0
	s_mov_b32 m0, s31
	v_lshl_add_u64 v[224:225], s[0:1], 0, v[150:151]
	ds_read_b128 v[176:179], v189 offset:32768
	ds_read_b128 v[180:183], v189 offset:33792
	ds_read_b128 v[184:187], v189 offset:34816
	ds_read_b128 v[190:193], v189 offset:35840
	ds_read_b128 v[202:205], v189 offset:36864
	ds_read_b128 v[206:209], v189 offset:37888
	ds_read_b128 v[210:213], v189 offset:38912
	ds_read_b128 v[214:217], v189 offset:39936
	global_load_lds_dwordx4 v[224:225], off
	v_lshl_add_u64 v[224:225], s[0:1], 0, v[152:153]
	s_mov_b32 m0, s34
	s_nop 0
	global_load_lds_dwordx4 v[224:225], off
	s_waitcnt vmcnt(8)
	s_waitcnt lgkmcnt(0)
	s_barrier
	s_setprio 1
	v_mfma_f32_16x16x32_bf16 v[126:129], v[130:133], v[176:179], v[126:129]
	v_mfma_f32_16x16x32_bf16 v[122:125], v[138:141], v[176:179], v[122:125]
	v_mfma_f32_16x16x32_bf16 v[110:113], v[130:133], v[184:187], v[110:113]
	v_mfma_f32_16x16x32_bf16 v[106:109], v[138:141], v[184:187], v[106:109]
	v_mfma_f32_16x16x32_bf16 v[98:101], v[130:133], v[202:205], v[98:101]
	v_mfma_f32_16x16x32_bf16 v[90:93], v[138:141], v[202:205], v[90:93]
	v_mfma_f32_16x16x32_bf16 v[82:85], v[130:133], v[210:213], v[82:85]
	v_mfma_f32_16x16x32_bf16 v[74:77], v[138:141], v[210:213], v[74:77]
	v_mfma_f32_16x16x32_bf16 v[126:129], v[134:137], v[180:183], v[126:129]
	v_mfma_f32_16x16x32_bf16 v[122:125], v[142:145], v[180:183], v[122:125]
	v_mfma_f32_16x16x32_bf16 v[110:113], v[134:137], v[190:193], v[110:113]
	v_mfma_f32_16x16x32_bf16 v[106:109], v[142:145], v[190:193], v[106:109]
	v_mfma_f32_16x16x32_bf16 v[98:101], v[134:137], v[206:209], v[98:101]
	v_mfma_f32_16x16x32_bf16 v[90:93], v[142:145], v[206:209], v[90:93]
	v_mfma_f32_16x16x32_bf16 v[82:85], v[134:137], v[214:217], v[82:85]
	v_mfma_f32_16x16x32_bf16 v[74:77], v[142:145], v[214:217], v[74:77]
	s_setprio 0
	s_setprio 1
	v_mfma_f32_16x16x32_bf16 v[118:121], v[146:149], v[176:179], v[118:121]
	v_mfma_f32_16x16x32_bf16 v[114:117], v[168:171], v[176:179], v[114:117]
	v_mfma_f32_16x16x32_bf16 v[102:105], v[146:149], v[184:187], v[102:105]
	v_mfma_f32_16x16x32_bf16 v[94:97], v[168:171], v[184:187], v[94:97]
	v_mfma_f32_16x16x32_bf16 v[86:89], v[146:149], v[202:205], v[86:89]
	v_mfma_f32_16x16x32_bf16 v[78:81], v[168:171], v[202:205], v[78:81]
	v_mfma_f32_16x16x32_bf16 v[70:73], v[146:149], v[210:213], v[70:73]
	v_mfma_f32_16x16x32_bf16 v[66:69], v[168:171], v[210:213], v[66:69]
	v_mfma_f32_16x16x32_bf16 v[118:121], v[164:167], v[180:183], v[118:121]
	v_mfma_f32_16x16x32_bf16 v[114:117], v[172:175], v[180:183], v[114:117]
	v_mfma_f32_16x16x32_bf16 v[102:105], v[164:167], v[190:193], v[102:105]
	v_mfma_f32_16x16x32_bf16 v[94:97], v[172:175], v[190:193], v[94:97]
	v_mfma_f32_16x16x32_bf16 v[86:89], v[164:167], v[206:209], v[86:89]
	v_mfma_f32_16x16x32_bf16 v[78:81], v[172:175], v[206:209], v[78:81]
	v_mfma_f32_16x16x32_bf16 v[70:73], v[164:167], v[214:217], v[70:73]
	v_mfma_f32_16x16x32_bf16 v[66:69], v[172:175], v[214:217], v[66:69]
	s_barrier
	s_setprio 0
	s_add_i32 s0, s46, s26
	v_lshl_add_u64 v[194:195], v[194:195], 0, s[16:17]
	s_mov_b32 m0, s0
	ds_read_b128 v[176:179], v189 offset:49152
	ds_read_b128 v[180:183], v189 offset:50176
	ds_read_b128 v[184:187], v189 offset:51200
	ds_read_b128 v[190:193], v189 offset:52224
	ds_read_b128 v[202:205], v189 offset:53248
	ds_read_b128 v[206:209], v189 offset:54272
	ds_read_b128 v[210:213], v189 offset:55296
	ds_read_b128 v[214:217], v189 offset:56320
	global_load_lds_dwordx4 v[194:195], off
	s_add_i32 m0, s0, 0x2000
	s_add_u32 s0, s48, 0x158080
	v_lshl_add_u64 v[194:195], v[218:219], 0, s[16:17]
	s_addc_u32 s1, s49, 0
	s_add_i32 s46, s47, s26
	global_load_lds_dwordx4 v[194:195], off
	v_lshl_add_u64 v[194:195], s[0:1], 0, v[196:197]
	s_mov_b32 m0, s46
	s_nop 0
	global_load_lds_dwordx4 v[194:195], off
	v_lshl_add_u64 v[194:195], s[0:1], 0, v[154:155]
	s_add_i32 m0, s46, 0x2000
	s_nop 0
	global_load_lds_dwordx4 v[194:195], off
	v_lshl_add_u64 v[194:195], v[220:221], 0, s[16:17]
	s_mov_b32 m0, s53
	s_nop 0
	global_load_lds_dwordx4 v[194:195], off
	v_lshl_add_u64 v[194:195], v[222:223], 0, s[16:17]
	s_mov_b32 m0, s58
	s_nop 0
	global_load_lds_dwordx4 v[194:195], off
	s_waitcnt vmcnt(8)
	s_waitcnt lgkmcnt(0)
	s_barrier
	s_setprio 1
	v_mfma_f32_16x16x32_bf16 v[62:65], v[130:133], v[176:179], v[62:65]
	v_mfma_f32_16x16x32_bf16 v[58:61], v[138:141], v[176:179], v[58:61]
	v_mfma_f32_16x16x32_bf16 v[50:53], v[130:133], v[184:187], v[50:53]
	v_mfma_f32_16x16x32_bf16 v[42:45], v[138:141], v[184:187], v[42:45]
	v_mfma_f32_16x16x32_bf16 v[34:37], v[130:133], v[202:205], v[34:37]
	v_mfma_f32_16x16x32_bf16 v[26:29], v[138:141], v[202:205], v[26:29]
	v_mfma_f32_16x16x32_bf16 v[18:21], v[130:133], v[210:213], v[18:21]
	v_mfma_f32_16x16x32_bf16 v[10:13], v[138:141], v[210:213], v[10:13]
	v_mfma_f32_16x16x32_bf16 v[62:65], v[134:137], v[180:183], v[62:65]
	v_mfma_f32_16x16x32_bf16 v[58:61], v[142:145], v[180:183], v[58:61]
	v_mfma_f32_16x16x32_bf16 v[50:53], v[134:137], v[190:193], v[50:53]
	v_mfma_f32_16x16x32_bf16 v[42:45], v[142:145], v[190:193], v[42:45]
	v_mfma_f32_16x16x32_bf16 v[34:37], v[134:137], v[206:209], v[34:37]
	v_mfma_f32_16x16x32_bf16 v[26:29], v[142:145], v[206:209], v[26:29]
	v_mfma_f32_16x16x32_bf16 v[18:21], v[134:137], v[214:217], v[18:21]
	v_mfma_f32_16x16x32_bf16 v[10:13], v[142:145], v[214:217], v[10:13]
	s_setprio 0
	s_setprio 1
	v_mfma_f32_16x16x32_bf16 v[54:57], v[146:149], v[176:179], v[54:57]
	v_mfma_f32_16x16x32_bf16 v[46:49], v[168:171], v[176:179], v[46:49]
	v_mfma_f32_16x16x32_bf16 v[38:41], v[146:149], v[184:187], v[38:41]
	v_mfma_f32_16x16x32_bf16 v[30:33], v[168:171], v[184:187], v[30:33]
	v_mfma_f32_16x16x32_bf16 v[22:25], v[146:149], v[202:205], v[22:25]
	v_mfma_f32_16x16x32_bf16 v[14:17], v[168:171], v[202:205], v[14:17]
	v_mfma_f32_16x16x32_bf16 v[6:9], v[146:149], v[210:213], v[6:9]
	v_mfma_f32_16x16x32_bf16 v[2:5], v[168:171], v[210:213], v[2:5]
	v_mfma_f32_16x16x32_bf16 v[54:57], v[164:167], v[180:183], v[54:57]
	v_mfma_f32_16x16x32_bf16 v[46:49], v[172:175], v[180:183], v[46:49]
	v_mfma_f32_16x16x32_bf16 v[38:41], v[164:167], v[190:193], v[38:41]
	v_mfma_f32_16x16x32_bf16 v[30:33], v[172:175], v[190:193], v[30:33]
	v_mfma_f32_16x16x32_bf16 v[22:25], v[164:167], v[206:209], v[22:25]
	v_mfma_f32_16x16x32_bf16 v[14:17], v[172:175], v[206:209], v[14:17]
	v_mfma_f32_16x16x32_bf16 v[6:9], v[164:167], v[214:217], v[6:9]
	v_mfma_f32_16x16x32_bf16 v[2:5], v[172:175], v[214:217], v[2:5]
	s_barrier
	s_setprio 0
	s_add_u32 s70, s70, 0x100
	s_addc_u32 s71, s71, 0
	s_cmp_ge_i32 s72, s69
	s_mov_b64 s[46:47], s[8:9]
	s_mov_b32 s48, s72
	s_cbranch_scc0 .LBB0_2588
	s_and_b64 vcc, exec, s[28:29]
	s_cbranch_vccz .LBB0_2591
	s_barrier
